# ConvGate epilogue: removed 51 s_nop pads before full-row DPP movs that no longer guard a hazard (leftovers of the removed zero-inits)
# baseline (speedup 1.0000x reference)
.LBB0_113:
	s_or_b64 exec, exec, s[0:1]
	v_ffbh_u32_e32 v0, v135
	v_min_u32_e32 v0, 32, v0
	v_lshlrev_b64 v[114:115], v0, v[134:135]
	v_min_u32_e32 v114, 1, v114
	v_or_b32_e32 v114, v115, v114
	v_cvt_f32_u32_e32 v114, v114
	v_sub_u32_e32 v0, 32, v0
	s_lshl_b32 s5, s78, 7
	v_add_u32_e32 v180, s5, v130
	v_ldexp_f32 v0, v114, v0
	v_fmamk_f32 v0, v0, 0x2e800000, v210
	s_nop 0
	v_rsq_f32_e32 v0, v0
	s_nop 0
	s_nop 0
	v_mov_b32_e32 v178, v0
	v_ffbh_u32_e32 v0, v133
	v_min_u32_e32 v0, 32, v0
	v_pk_mul_f32 v[186:187], v[110:111], v[178:179] op_sel_hi:[1,0]
	v_lshlrev_b64 v[110:111], v0, v[132:133]
	v_min_u32_e32 v110, 1, v110
	v_or_b32_e32 v110, v111, v110
	v_cvt_f32_u32_e32 v110, v110
	v_sub_u32_e32 v0, 32, v0
	v_pk_mul_f32 v[184:185], v[112:113], v[178:179] op_sel_hi:[1,0]
	v_ldexp_f32 v0, v110, v0
	v_fmamk_f32 v0, v0, 0x2e800000, v210
	s_nop 0
	v_rsq_f32_e32 v0, v0
	s_nop 0
	s_nop 0
	v_mov_b32_e32 v182, v0
	v_pk_mul_f32 v[188:189], v[108:109], v[182:183] op_sel_hi:[1,0]
	v_pk_mul_f32 v[198:199], v[106:107], v[182:183] op_sel_hi:[1,0]
	v_ashrrev_i32_e32 v181, 31, v180
	v_lshlrev_b64 v[118:119], 2, v[180:181]
	v_lshl_add_u64 v[106:107], s[44:45], 0, v[118:119]
	v_lshl_add_u64 v[108:109], s[60:61], 0, v[118:119]
	global_load_dwordx4 v[122:125], v[106:107], off
	global_load_dwordx4 v[126:129], v[108:109], off
	v_lshl_add_u64 v[106:107], s[2:3], 0, v[118:119]
	global_load_dwordx4 v[130:133], v[106:107], off
	v_lshl_add_u64 v[106:107], s[48:49], 0, v[118:119]
	global_load_dwordx4 v[134:137], v[106:107], off
	s_nop 1
	v_cmp_lt_u32_e32 vcc, 1, v183
	v_mov_b32_dpp v206, v170 row_ror:1 row_mask:0xf bank_mask:0xf
	v_mov_b32_dpp v204, v170 row_ror:2 row_mask:0xf bank_mask:0xf
	v_mov_b32_dpp v207, v171 row_ror:1 row_mask:0xf bank_mask:0xf
	v_mov_b32_dpp v205, v171 row_ror:2 row_mask:0xf bank_mask:0xf
	v_mov_b32_dpp v202, v172 row_ror:1 row_mask:0xf bank_mask:0xf
	v_mov_b32_dpp v200, v172 row_ror:2 row_mask:0xf bank_mask:0xf
	v_mov_b32_dpp v203, v173 row_ror:1 row_mask:0xf bank_mask:0xf
	v_mov_b32_dpp v201, v173 row_ror:2 row_mask:0xf bank_mask:0xf
	v_mov_b32_dpp v241, v186 row_ror:1 row_mask:0xf bank_mask:0xf
	v_mov_b32_dpp v240, v186 row_ror:2 row_mask:0xf bank_mask:0xf
	v_mov_b32_dpp v245, v187 row_ror:1 row_mask:0xf bank_mask:0xf
	v_mov_b32_dpp v244, v187 row_ror:2 row_mask:0xf bank_mask:0xf
	v_mov_b32_dpp v229, v184 row_ror:1 row_mask:0xf bank_mask:0xf
	v_mov_b32_dpp v228, v184 row_ror:2 row_mask:0xf bank_mask:0xf
	v_mov_b32_dpp v235, v185 row_ror:1 row_mask:0xf bank_mask:0xf
	v_mov_b32_dpp v233, v185 row_ror:2 row_mask:0xf bank_mask:0xf
	v_mov_b32_dpp v234, v198 row_ror:1 row_mask:0xf bank_mask:0xf
	v_mov_b32_dpp v231, v198 row_ror:2 row_mask:0xf bank_mask:0xf
	v_mov_b32_dpp v239, v199 row_ror:1 row_mask:0xf bank_mask:0xf
	v_mov_b32_dpp v237, v199 row_ror:2 row_mask:0xf bank_mask:0xf
	v_mov_b32_dpp v151, v188 row_ror:1 row_mask:0xf bank_mask:0xf
	v_mov_b32_dpp v0, v188 row_ror:2 row_mask:0xf bank_mask:0xf
	v_mov_b32_dpp v227, v189 row_ror:1 row_mask:0xf bank_mask:0xf
	v_mov_b32_dpp v213, v189 row_ror:2 row_mask:0xf bank_mask:0xf
	v_mov_b32_dpp v243, v176 row_ror:1 row_mask:0xf bank_mask:0xf
	v_mov_b32_dpp v242, v176 row_ror:2 row_mask:0xf bank_mask:0xf
	v_mov_b32_dpp v247, v177 row_ror:1 row_mask:0xf bank_mask:0xf
	v_mov_b32_dpp v246, v177 row_ror:2 row_mask:0xf bank_mask:0xf
	v_mov_b32_dpp v232, v174 row_ror:1 row_mask:0xf bank_mask:0xf
	v_mov_b32_dpp v230, v174 row_ror:2 row_mask:0xf bank_mask:0xf
	v_mov_b32_dpp v238, v175 row_ror:1 row_mask:0xf bank_mask:0xf
	v_mov_b32_dpp v236, v175 row_ror:2 row_mask:0xf bank_mask:0xf
	v_lshl_add_u64 v[106:107], s[96:97], 0, v[118:119]
	v_lshl_add_u64 v[108:109], s[62:63], 0, v[118:119]
	global_load_dwordx4 v[114:117], v[106:107], off
	global_load_dwordx4 v[110:113], v[108:109], off
	v_lshl_add_u64 v[106:107], s[64:65], 0, v[118:119]
	v_lshl_add_u64 v[118:119], s[66:67], 0, v[118:119]
	global_load_dwordx4 v[106:109], v[106:107], off
	s_nop 1
	global_load_dwordx4 v[118:121], v[118:119], off
	v_mov_b32_dpp v190, v158 row_ror:1 row_mask:0xf bank_mask:0xf
	v_mov_b32_dpp v194, v158 row_ror:2 row_mask:0xf bank_mask:0xf
	v_mov_b32_dpp v191, v159 row_ror:1 row_mask:0xf bank_mask:0xf
	v_mov_b32_dpp v195, v159 row_ror:2 row_mask:0xf bank_mask:0xf
	v_mov_b32_dpp v192, v156 row_ror:1 row_mask:0xf bank_mask:0xf
	v_mov_b32_dpp v196, v156 row_ror:2 row_mask:0xf bank_mask:0xf
	v_mov_b32_dpp v193, v157 row_ror:1 row_mask:0xf bank_mask:0xf
	v_mov_b32_dpp v197, v157 row_ror:2 row_mask:0xf bank_mask:0xf
	s_and_saveexec_b64 s[0:1], vcc
	s_mov_b32 s50, 0x20000
	s_mov_b32 s47, 0xbfb8aa3b
	s_cbranch_execz .Lcg_skip0
	s_waitcnt vmcnt(4)
	v_pk_fma_f32 v[248:249], v[124:125], v[200:201], v[136:137]
	s_nop 0
	v_pk_fma_f32 v[248:249], v[128:129], v[202:203], v[248:249]
	s_nop 0
	v_pk_fma_f32 v[172:173], v[172:173], v[132:133], v[248:249]
	v_pk_fma_f32 v[248:249], v[122:123], v[204:205], v[134:135]
	v_pk_fma_f32 v[248:249], v[126:127], v[206:207], v[248:249]
	v_pk_fma_f32 v[170:171], v[170:171], v[130:131], v[248:249]
	v_pk_mul_f32 v[248:249], v[170:171], s[98:99] op_sel_hi:[1,0]
	v_pk_mul_f32 v[250:251], v[172:173], s[98:99] op_sel_hi:[1,0]
	v_exp_f32_e32 v248, v248
	v_exp_f32_e32 v249, v249
	v_exp_f32_e32 v250, v250
	v_exp_f32_e32 v251, v251
	v_pk_add_f32 v[248:249], v[248:249], 1.0 op_sel_hi:[1,0]
	v_pk_add_f32 v[250:251], v[250:251], 1.0 op_sel_hi:[1,0]
	v_rcp_f32_e32 v248, v248
	v_rcp_f32_e32 v249, v249
	v_rcp_f32_e32 v250, v250
	v_rcp_f32_e32 v251, v251
	v_pk_mul_f32 v[170:171], v[170:171], v[248:249]
	v_pk_mul_f32 v[172:173], v[172:173], v[250:251]
	s_waitcnt vmcnt(0)
	v_pk_fma_f32 v[248:249], v[116:117], v[196:197], v[120:121]
	v_pk_fma_f32 v[250:251], v[114:115], v[194:195], v[118:119]
	v_pk_fma_f32 v[248:249], v[112:113], v[192:193], v[248:249]
	v_pk_fma_f32 v[250:251], v[110:111], v[190:191], v[250:251]
	v_pk_fma_f32 v[156:157], v[156:157], v[108:109], v[248:249]
	v_pk_fma_f32 v[158:159], v[158:159], v[106:107], v[250:251]
	v_pk_mul_f32 v[156:157], v[172:173], v[156:157]
	v_pk_mul_f32 v[158:159], v[170:171], v[158:159]
	s_nop 0
	v_cvt_pk_bf16_f32 v158, v158, v159
	v_cvt_pk_bf16_f32 v159, v156, v157
	v_mov_b64_e32 v[156:157], s[36:37]
	v_mad_i64_i32 v[156:157], s[28:29], v150, s46, v[156:157]
	v_lshl_add_u64 v[156:157], v[180:181], 1, v[156:157]
	global_store_dwordx2 v[156:157], v[158:159], off
.LBB0_115:
	s_or_b64 exec, exec, s[0:1]
	v_cmp_eq_u32_e64 s[42:43], 0, v183
	v_cndmask_b32_e32 v159, v205, v244, vcc
	v_cndmask_b32_e32 v158, v204, v240, vcc
	v_cndmask_b32_e64 v157, v245, v207, s[42:43]
	v_cndmask_b32_e64 v156, v241, v206, s[42:43]
	s_waitcnt vmcnt(4)
	v_pk_fma_f32 v[158:159], v[122:123], v[158:159], v[134:135]
	v_cndmask_b32_e32 v173, v201, v233, vcc
	v_cndmask_b32_e32 v172, v200, v228, vcc
	v_pk_fma_f32 v[156:157], v[126:127], v[156:157], v[158:159]
	v_cndmask_b32_e64 v171, v235, v203, s[42:43]
	v_cndmask_b32_e64 v170, v229, v202, s[42:43]
	v_pk_fma_f32 v[172:173], v[124:125], v[172:173], v[136:137]
	v_pk_fma_f32 v[156:157], v[186:187], v[130:131], v[156:157]
	v_pk_fma_f32 v[170:171], v[128:129], v[170:171], v[172:173]
	v_cndmask_b32_e32 v187, v244, v237, vcc
	v_cndmask_b32_e32 v186, v240, v231, vcc
	v_pk_fma_f32 v[170:171], v[184:185], v[132:133], v[170:171]
	v_cndmask_b32_e64 v185, v239, v245, s[42:43]
	v_cndmask_b32_e64 v184, v234, v241, s[42:43]
	v_pk_fma_f32 v[186:187], v[122:123], v[186:187], v[134:135]
	v_cndmask_b32_e32 v201, v233, v213, vcc
	v_pk_fma_f32 v[184:185], v[126:127], v[184:185], v[186:187]
	v_cndmask_b32_e32 v200, v228, v0, vcc
	v_pk_fma_f32 v[184:185], v[198:199], v[130:131], v[184:185]
	v_cndmask_b32_e64 v199, v227, v235, s[42:43]
	v_cndmask_b32_e64 v198, v151, v229, s[42:43]
	v_pk_fma_f32 v[200:201], v[124:125], v[200:201], v[136:137]
	v_cndmask_b32_e32 v203, v237, v246, vcc
	v_cndmask_b32_e32 v202, v231, v242, vcc
	v_pk_fma_f32 v[198:199], v[128:129], v[198:199], v[200:201]
	v_cndmask_b32_e64 v201, v247, v239, s[42:43]
	v_cndmask_b32_e64 v200, v243, v234, s[42:43]
	v_pk_fma_f32 v[122:123], v[122:123], v[202:203], v[134:135]
	v_cndmask_b32_e32 v135, v213, v236, vcc
	v_pk_fma_f32 v[122:123], v[126:127], v[200:201], v[122:123]
	v_cndmask_b32_e32 v134, v0, v230, vcc
	v_pk_fma_f32 v[122:123], v[176:177], v[130:131], v[122:123]
	v_cndmask_b32_e64 v131, v238, v227, s[42:43]
	v_cndmask_b32_e64 v130, v232, v151, s[42:43]
	v_pk_fma_f32 v[124:125], v[124:125], v[134:135], v[136:137]
	v_pk_fma_f32 v[124:125], v[128:129], v[130:131], v[124:125]
	v_mov_b32_e32 v179, v178
	v_pk_fma_f32 v[124:125], v[174:175], v[132:133], v[124:125]
	v_mov_b32_e32 v183, v182
	v_mov_b32_e32 v130, v178
	v_mov_b32_e32 v131, v178
	v_pk_mul_f32 v[104:105], v[104:105], v[130:131]
	v_pk_mul_f32 v[102:103], v[102:103], v[178:179]
	v_pk_mul_f32 v[98:99], v[98:99], v[182:183]
	s_nop 1
	v_mov_b32_e32 v130, v182
	v_mov_b32_e32 v131, v182
	v_mov_b32_dpp v177, v102 row_ror:2 row_mask:0xf bank_mask:0xf
	v_mov_b32_dpp v179, v103 row_ror:2 row_mask:0xf bank_mask:0xf
	v_mov_b32_dpp v183, v104 row_ror:2 row_mask:0xf bank_mask:0xf
	v_mov_b32_dpp v201, v105 row_ror:2 row_mask:0xf bank_mask:0xf
	v_pk_fma_f32 v[188:189], v[188:189], v[132:133], v[198:199]
	v_pk_mul_f32 v[100:101], v[100:101], v[130:131]
	v_mov_b32_dpp v176, v102 row_ror:1 row_mask:0xf bank_mask:0xf
	v_mov_b32_dpp v178, v103 row_ror:1 row_mask:0xf bank_mask:0xf
	v_mov_b32_dpp v182, v104 row_ror:1 row_mask:0xf bank_mask:0xf
	v_mov_b32_dpp v200, v105 row_ror:1 row_mask:0xf bank_mask:0xf
	v_cndmask_b32_e32 v130, v194, v177, vcc
	v_cndmask_b32_e32 v131, v195, v179, vcc
	v_cndmask_b32_e32 v132, v196, v183, vcc
	v_cndmask_b32_e32 v133, v197, v201, vcc
	v_cndmask_b32_e64 v134, v176, v190, s[42:43]
	v_cndmask_b32_e64 v135, v178, v191, s[42:43]
	v_cndmask_b32_e64 v136, v182, v192, s[42:43]
	v_cndmask_b32_e64 v137, v200, v193, s[42:43]
	s_waitcnt vmcnt(1)
	v_pk_fma_f32 v[132:133], v[116:117], v[132:133], v[120:121]
	v_pk_fma_f32 v[130:131], v[114:115], v[130:131], v[118:119]
	v_pk_fma_f32 v[132:133], v[112:113], v[136:137], v[132:133]
	v_pk_fma_f32 v[130:131], v[110:111], v[134:135], v[130:131]
	v_or_b32_e32 v0, 16, v150
	v_or_b32_e32 v174, 32, v150
	v_or_b32_e32 v175, 48, v150
	v_pk_mul_f32 v[158:159], v[156:157], s[98:99] op_sel_hi:[1,0]
	v_pk_mul_f32 v[172:173], v[170:171], s[98:99] op_sel_hi:[1,0]
	v_exp_f32_e32 v158, v158
	v_exp_f32_e32 v159, v159
	v_exp_f32_e32 v172, v172
	v_exp_f32_e32 v173, v173
	v_pk_add_f32 v[158:159], v[158:159], 1.0 op_sel_hi:[1,0]
	v_pk_add_f32 v[172:173], v[172:173], 1.0 op_sel_hi:[1,0]
	v_rcp_f32_e32 v158, v158
	v_rcp_f32_e32 v159, v159
	v_rcp_f32_e32 v172, v172
	v_rcp_f32_e32 v173, v173
	v_pk_mul_f32 v[150:151], v[156:157], v[158:159]
	v_pk_mul_f32 v[156:157], v[170:171], v[172:173]
	v_pk_fma_f32 v[104:105], v[104:105], v[108:109], v[132:133]
	v_pk_fma_f32 v[102:103], v[102:103], v[106:107], v[130:131]
	v_pk_mul_f32 v[104:105], v[156:157], v[104:105]
	v_pk_mul_f32 v[102:103], v[150:151], v[102:103]
	v_cvt_pk_bf16_f32 v102, v102, v103
	v_cvt_pk_bf16_f32 v103, v104, v105
	v_mov_b64_e32 v[104:105], s[36:37]
	v_mad_i64_i32 v[130:131], s[0:1], v0, s46, v[104:105]
	v_lshlrev_b64 v[132:133], 1, v[180:181]
	s_nop 1
	v_lshl_add_u64 v[130:131], v[130:131], 0, v[132:133]
	v_mov_b32_dpp v158, v98 row_ror:2 row_mask:0xf bank_mask:0xf
	v_mov_b32_dpp v170, v99 row_ror:2 row_mask:0xf bank_mask:0xf
	v_mov_b32_dpp v172, v100 row_ror:2 row_mask:0xf bank_mask:0xf
	v_mov_b32_dpp v180, v101 row_ror:2 row_mask:0xf bank_mask:0xf
	global_store_dwordx2 v[130:131], v[102:103], off
	v_mov_b32_dpp v0, v98 row_ror:1 row_mask:0xf bank_mask:0xf
	v_mov_b32_dpp v159, v99 row_ror:1 row_mask:0xf bank_mask:0xf
	v_mov_b32_dpp v171, v100 row_ror:1 row_mask:0xf bank_mask:0xf
	v_mov_b32_dpp v173, v101 row_ror:1 row_mask:0xf bank_mask:0xf
	v_cndmask_b32_e32 v102, v177, v158, vcc
	v_cndmask_b32_e32 v103, v179, v170, vcc
	v_cndmask_b32_e32 v130, v183, v172, vcc
	v_cndmask_b32_e32 v131, v201, v180, vcc
	v_cndmask_b32_e64 v134, v0, v176, s[42:43]
	v_cndmask_b32_e64 v135, v159, v178, s[42:43]
	v_cndmask_b32_e64 v136, v171, v182, s[42:43]
	v_cndmask_b32_e64 v137, v173, v200, s[42:43]
	v_pk_fma_f32 v[130:131], v[116:117], v[130:131], v[120:121]
	v_pk_fma_f32 v[102:103], v[114:115], v[102:103], v[118:119]
	v_pk_fma_f32 v[130:131], v[112:113], v[136:137], v[130:131]
	v_pk_fma_f32 v[102:103], v[110:111], v[134:135], v[102:103]
	v_pk_mul_f32 v[186:187], v[184:185], s[98:99] op_sel_hi:[1,0]
	v_pk_mul_f32 v[198:199], v[188:189], s[98:99] op_sel_hi:[1,0]
	v_exp_f32_e32 v186, v186
	v_exp_f32_e32 v187, v187
	v_exp_f32_e32 v198, v198
	v_exp_f32_e32 v199, v199
	v_pk_add_f32 v[186:187], v[186:187], 1.0 op_sel_hi:[1,0]
	v_pk_add_f32 v[198:199], v[198:199], 1.0 op_sel_hi:[1,0]
	v_rcp_f32_e32 v186, v186
	v_rcp_f32_e32 v187, v187
	v_rcp_f32_e32 v198, v198
	v_rcp_f32_e32 v199, v199
	v_pk_mul_f32 v[150:151], v[184:185], v[186:187]
	v_pk_mul_f32 v[156:157], v[188:189], v[198:199]
	v_pk_fma_f32 v[100:101], v[100:101], v[108:109], v[130:131]
	v_pk_fma_f32 v[98:99], v[98:99], v[106:107], v[102:103]
	v_pk_mul_f32 v[100:101], v[156:157], v[100:101]
	v_pk_mul_f32 v[98:99], v[150:151], v[98:99]
	v_cvt_pk_bf16_f32 v98, v98, v99
	v_cvt_pk_bf16_f32 v99, v100, v101
	v_mad_i64_i32 v[100:101], s[0:1], v174, s46, v[104:105]
	v_lshl_add_u64 v[100:101], v[100:101], 0, v[132:133]
	global_store_dwordx2 v[100:101], v[98:99], off
	s_nop 1
	v_mov_b32_dpp v98, v154 row_ror:2 row_mask:0xf bank_mask:0xf
	v_mov_b32_dpp v99, v155 row_ror:2 row_mask:0xf bank_mask:0xf
	v_mov_b32_dpp v100, v152 row_ror:2 row_mask:0xf bank_mask:0xf
	v_mov_b32_dpp v101, v153 row_ror:2 row_mask:0xf bank_mask:0xf
	v_mov_b32_dpp v102, v154 row_ror:1 row_mask:0xf bank_mask:0xf
	v_mov_b32_dpp v103, v155 row_ror:1 row_mask:0xf bank_mask:0xf
	v_mov_b32_dpp v130, v152 row_ror:1 row_mask:0xf bank_mask:0xf
	v_mov_b32_dpp v131, v153 row_ror:1 row_mask:0xf bank_mask:0xf
	v_cndmask_b32_e32 v98, v158, v98, vcc
	v_cndmask_b32_e32 v99, v170, v99, vcc
	v_cndmask_b32_e32 v100, v172, v100, vcc
	v_cndmask_b32_e32 v101, v180, v101, vcc
	v_cndmask_b32_e64 v102, v102, v0, s[42:43]
	v_cndmask_b32_e64 v103, v103, v159, s[42:43]
	v_cndmask_b32_e64 v130, v130, v171, s[42:43]
	v_cndmask_b32_e64 v131, v131, v173, s[42:43]
	v_pk_fma_f32 v[98:99], v[114:115], v[98:99], v[118:119]
	v_pk_fma_f32 v[100:101], v[116:117], v[100:101], v[120:121]
	v_pk_fma_f32 v[98:99], v[110:111], v[102:103], v[98:99]
	v_pk_fma_f32 v[100:101], v[112:113], v[130:131], v[100:101]
	v_pk_mul_f32 v[126:127], v[122:123], s[98:99] op_sel_hi:[1,0]
	v_pk_mul_f32 v[128:129], v[124:125], s[98:99] op_sel_hi:[1,0]
	v_exp_f32_e32 v126, v126
	v_exp_f32_e32 v127, v127
	v_exp_f32_e32 v128, v128
	v_exp_f32_e32 v129, v129
	v_pk_add_f32 v[126:127], v[126:127], 1.0 op_sel_hi:[1,0]
	v_pk_add_f32 v[128:129], v[128:129], 1.0 op_sel_hi:[1,0]
	v_rcp_f32_e32 v126, v126
	v_rcp_f32_e32 v127, v127
	v_rcp_f32_e32 v128, v128
	v_rcp_f32_e32 v129, v129
	v_pk_mul_f32 v[122:123], v[122:123], v[126:127]
	v_pk_mul_f32 v[124:125], v[124:125], v[128:129]
	v_pk_fma_f32 v[98:99], v[154:155], v[106:107], v[98:99]
	v_pk_fma_f32 v[100:101], v[152:153], v[108:109], v[100:101]
	v_pk_mul_f32 v[98:99], v[122:123], v[98:99]
	v_pk_mul_f32 v[100:101], v[124:125], v[100:101]
	v_cvt_pk_bf16_f32 v98, v98, v99
	s_nop 0
	v_cvt_pk_bf16_f32 v99, v100, v101
	v_mad_i64_i32 v[100:101], s[0:1], v175, s46, v[104:105]
	v_lshl_add_u64 v[100:101], v[100:101], 0, v[132:133]
	global_store_dwordx2 v[100:101], v[98:99], off
	s_add_i32 s0, s6, 2
	v_and_b32_e32 v129, 15, v226
	v_or_b32_e32 v106, s4, v129
	v_ashrrev_i32_e32 v107, 31, v106
	v_lshl_add_u64 v[104:105], v[106:107], 3, s[38:39]
	global_load_dwordx2 v[108:109], v[104:105], off offset:1024
	global_load_dwordx2 v[102:103], v[104:105], off offset:1152
	global_load_dwordx2 v[100:101], v[104:105], off offset:1280
	s_nop 0
	global_load_dwordx2 v[104:105], v[104:105], off offset:1408
	v_ashrrev_i32_e32 v0, 1, v226
	v_and_b32_e32 v0, -8, v0
	v_add_u32_e32 v98, s21, v0
	s_mul_hi_i32 s1, s0, 0xb000
	s_mul_i32 s0, s0, 0xb000
	s_add_u32 s0, s18, s0
	s_addc_u32 s1, s19, s1
	s_add_u32 s78, s0, s80
	s_addc_u32 s79, s1, s81
	s_waitcnt vmcnt(3)
	v_ffbh_u32_e32 v0, v109
	v_min_u32_e32 v0, 32, v0
	v_lshlrev_b64 v[108:109], v0, v[108:109]
	v_min_u32_e32 v99, 1, v108
	v_or_b32_e32 v99, v109, v99
	v_cvt_f32_u32_e32 v99, v99
	v_sub_u32_e32 v0, 32, v0
	v_ldexp_f32 v0, v99, v0
	v_fmamk_f32 v0, v0, 0x2e800000, v210
	s_nop 0
	v_rsq_f32_e32 v0, v0
	s_nop 0
	s_nop 0
	v_ashrrev_i32_e32 v99, 31, v98
	v_pk_mul_f32 v[118:119], v[96:97], v[0:1] op_sel_hi:[1,0]
	v_pk_mul_f32 v[116:117], v[94:95], v[0:1] op_sel_hi:[1,0]
	v_pk_mul_f32 v[112:113], v[92:93], v[0:1] op_sel_hi:[1,0]
	v_pk_mul_f32 v[114:115], v[90:91], v[0:1] op_sel_hi:[1,0]
	v_lshl_add_u64 v[90:91], v[98:99], 1, s[78:79]
	v_cmp_gt_u32_e32 vcc, 2, v129
	s_and_saveexec_b64 s[0:1], vcc
	s_cbranch_execz .LBB0_117
	v_mul_u32_u24_e32 v0, 0x1600, v129
	v_lshlrev_b32_e32 v0, 1, v0
	v_cvt_pk_bf16_f32 v92, v116, v117
	v_cvt_pk_bf16_f32 v93, v118, v119
	v_lshl_add_u64 v[96:97], v[90:91], 0, v[0:1]
	v_cvt_pk_bf16_f32 v94, v114, v115
	v_cvt_pk_bf16_f32 v95, v112, v113
	global_store_dwordx2 v[96:97], v[92:93], off
	global_store_dwordx2 v[96:97], v[94:95], off offset:256

.LBB0_119:
	s_or_b64 exec, exec, s[0:1]
	v_ffbh_u32_e32 v0, v103
	v_min_u32_e32 v0, 32, v0
	v_lshlrev_b64 v[82:83], v0, v[102:103]
	v_min_u32_e32 v82, 1, v82
	v_or_b32_e32 v82, v83, v82
	v_cvt_f32_u32_e32 v82, v82
	v_sub_u32_e32 v0, 32, v0
	v_add_u32_e32 v126, s5, v98
	v_ldexp_f32 v0, v82, v0
	v_fmamk_f32 v0, v0, 0x2e800000, v210
	s_nop 0
	v_rsq_f32_e32 v0, v0
	s_nop 0
	s_nop 0
	v_mov_b32_e32 v124, v0
	v_ffbh_u32_e32 v0, v101
	v_min_u32_e32 v0, 32, v0
	v_pk_mul_f32 v[132:133], v[78:79], v[124:125] op_sel_hi:[1,0]
	v_lshlrev_b64 v[78:79], v0, v[100:101]
	v_min_u32_e32 v78, 1, v78
	v_or_b32_e32 v78, v79, v78
	v_cvt_f32_u32_e32 v78, v78
	v_sub_u32_e32 v0, 32, v0
	v_pk_mul_f32 v[130:131], v[80:81], v[124:125] op_sel_hi:[1,0]
	v_ldexp_f32 v0, v78, v0
	v_fmamk_f32 v0, v0, 0x2e800000, v210
	s_nop 0
	v_rsq_f32_e32 v0, v0
	s_nop 0
	s_nop 0
	v_mov_b32_e32 v128, v0
	v_pk_mul_f32 v[134:135], v[76:77], v[128:129] op_sel_hi:[1,0]
	v_pk_mul_f32 v[156:157], v[74:75], v[128:129] op_sel_hi:[1,0]
	v_ashrrev_i32_e32 v127, 31, v126
	v_lshlrev_b64 v[86:87], 2, v[126:127]
	v_lshl_add_u64 v[74:75], s[44:45], 0, v[86:87]
	v_lshl_add_u64 v[76:77], s[60:61], 0, v[86:87]
	global_load_dwordx4 v[90:93], v[74:75], off
	global_load_dwordx4 v[94:97], v[76:77], off
	v_lshl_add_u64 v[74:75], s[2:3], 0, v[86:87]
	global_load_dwordx4 v[98:101], v[74:75], off
	v_lshl_add_u64 v[74:75], s[48:49], 0, v[86:87]
	global_load_dwordx4 v[102:105], v[74:75], off
	s_nop 1
	v_cmp_lt_u32_e32 vcc, 1, v129
	v_mov_b32_dpp v174, v116 row_ror:1 row_mask:0xf bank_mask:0xf
	v_mov_b32_dpp v172, v116 row_ror:2 row_mask:0xf bank_mask:0xf
	v_mov_b32_dpp v175, v117 row_ror:1 row_mask:0xf bank_mask:0xf
	v_mov_b32_dpp v173, v117 row_ror:2 row_mask:0xf bank_mask:0xf
	v_mov_b32_dpp v170, v118 row_ror:1 row_mask:0xf bank_mask:0xf
	v_mov_b32_dpp v158, v118 row_ror:2 row_mask:0xf bank_mask:0xf
	v_mov_b32_dpp v171, v119 row_ror:1 row_mask:0xf bank_mask:0xf
	v_mov_b32_dpp v159, v119 row_ror:2 row_mask:0xf bank_mask:0xf
	v_mov_b32_dpp v191, v132 row_ror:1 row_mask:0xf bank_mask:0xf
	v_mov_b32_dpp v190, v132 row_ror:2 row_mask:0xf bank_mask:0xf
	v_mov_b32_dpp v195, v133 row_ror:1 row_mask:0xf bank_mask:0xf
	v_mov_b32_dpp v194, v133 row_ror:2 row_mask:0xf bank_mask:0xf
	v_mov_b32_dpp v179, v130 row_ror:1 row_mask:0xf bank_mask:0xf
	v_mov_b32_dpp v178, v130 row_ror:2 row_mask:0xf bank_mask:0xf
	v_mov_b32_dpp v185, v131 row_ror:1 row_mask:0xf bank_mask:0xf
	v_mov_b32_dpp v183, v131 row_ror:2 row_mask:0xf bank_mask:0xf
	v_mov_b32_dpp v184, v156 row_ror:1 row_mask:0xf bank_mask:0xf
	v_mov_b32_dpp v181, v156 row_ror:2 row_mask:0xf bank_mask:0xf
	v_mov_b32_dpp v189, v157 row_ror:1 row_mask:0xf bank_mask:0xf
	v_mov_b32_dpp v187, v157 row_ror:2 row_mask:0xf bank_mask:0xf
	v_mov_b32_dpp v107, v134 row_ror:1 row_mask:0xf bank_mask:0xf
	v_mov_b32_dpp v0, v134 row_ror:2 row_mask:0xf bank_mask:0xf
	v_mov_b32_dpp v177, v135 row_ror:1 row_mask:0xf bank_mask:0xf
	v_mov_b32_dpp v176, v135 row_ror:2 row_mask:0xf bank_mask:0xf
	v_mov_b32_dpp v193, v122 row_ror:1 row_mask:0xf bank_mask:0xf
	v_mov_b32_dpp v192, v122 row_ror:2 row_mask:0xf bank_mask:0xf
	v_mov_b32_dpp v197, v123 row_ror:1 row_mask:0xf bank_mask:0xf
	v_mov_b32_dpp v196, v123 row_ror:2 row_mask:0xf bank_mask:0xf
	v_mov_b32_dpp v182, v120 row_ror:1 row_mask:0xf bank_mask:0xf
	v_mov_b32_dpp v180, v120 row_ror:2 row_mask:0xf bank_mask:0xf
	v_mov_b32_dpp v188, v121 row_ror:1 row_mask:0xf bank_mask:0xf
	v_mov_b32_dpp v186, v121 row_ror:2 row_mask:0xf bank_mask:0xf
	v_lshl_add_u64 v[74:75], s[96:97], 0, v[86:87]
	v_lshl_add_u64 v[76:77], s[62:63], 0, v[86:87]
	global_load_dwordx4 v[82:85], v[74:75], off
	global_load_dwordx4 v[78:81], v[76:77], off
	v_lshl_add_u64 v[74:75], s[64:65], 0, v[86:87]
	v_lshl_add_u64 v[86:87], s[66:67], 0, v[86:87]
	global_load_dwordx4 v[74:77], v[74:75], off
	s_nop 1
	global_load_dwordx4 v[86:89], v[86:87], off
	v_mov_b32_dpp v136, v114 row_ror:1 row_mask:0xf bank_mask:0xf
	v_mov_b32_dpp v152, v114 row_ror:2 row_mask:0xf bank_mask:0xf
	v_mov_b32_dpp v137, v115 row_ror:1 row_mask:0xf bank_mask:0xf
	v_mov_b32_dpp v153, v115 row_ror:2 row_mask:0xf bank_mask:0xf
	v_mov_b32_dpp v150, v112 row_ror:1 row_mask:0xf bank_mask:0xf
	v_mov_b32_dpp v154, v112 row_ror:2 row_mask:0xf bank_mask:0xf
	v_mov_b32_dpp v151, v113 row_ror:1 row_mask:0xf bank_mask:0xf
	v_mov_b32_dpp v155, v113 row_ror:2 row_mask:0xf bank_mask:0xf
	s_and_saveexec_b64 s[0:1], vcc
	s_cbranch_execz .Lcg_skip1
	s_waitcnt vmcnt(4)
	v_pk_fma_f32 v[198:199], v[92:93], v[158:159], v[104:105]
	s_nop 0
	v_pk_fma_f32 v[198:199], v[96:97], v[170:171], v[198:199]
	s_nop 0
	v_pk_fma_f32 v[118:119], v[118:119], v[100:101], v[198:199]
	v_pk_fma_f32 v[198:199], v[90:91], v[172:173], v[102:103]
	v_pk_fma_f32 v[198:199], v[94:95], v[174:175], v[198:199]
	v_pk_fma_f32 v[116:117], v[116:117], v[98:99], v[198:199]
	v_add_u32_e32 v125, 0x80, v106
	v_pk_mul_f32 v[198:199], v[116:117], s[98:99] op_sel_hi:[1,0]
	v_pk_mul_f32 v[200:201], v[118:119], s[98:99] op_sel_hi:[1,0]
	v_exp_f32_e32 v198, v198
	v_exp_f32_e32 v199, v199
	v_exp_f32_e32 v200, v200
	v_exp_f32_e32 v201, v201
	v_pk_add_f32 v[198:199], v[198:199], 1.0 op_sel_hi:[1,0]
	v_pk_add_f32 v[200:201], v[200:201], 1.0 op_sel_hi:[1,0]
	v_rcp_f32_e32 v198, v198
	v_rcp_f32_e32 v199, v199
	v_rcp_f32_e32 v200, v200
	v_rcp_f32_e32 v201, v201
	v_pk_mul_f32 v[116:117], v[116:117], v[198:199]
	v_pk_mul_f32 v[118:119], v[118:119], v[200:201]
	s_waitcnt vmcnt(0)
	v_pk_fma_f32 v[198:199], v[84:85], v[154:155], v[88:89]
	v_pk_fma_f32 v[200:201], v[82:83], v[152:153], v[86:87]
	v_pk_fma_f32 v[198:199], v[80:81], v[150:151], v[198:199]
	v_pk_fma_f32 v[200:201], v[78:79], v[136:137], v[200:201]
	v_pk_fma_f32 v[112:113], v[112:113], v[76:77], v[198:199]
	v_pk_fma_f32 v[114:115], v[114:115], v[74:75], v[200:201]
	v_pk_mul_f32 v[112:113], v[118:119], v[112:113]
	v_pk_mul_f32 v[114:115], v[116:117], v[114:115]
	s_nop 0
	v_cvt_pk_bf16_f32 v114, v114, v115
	v_cvt_pk_bf16_f32 v115, v112, v113
	v_mov_b64_e32 v[112:113], s[36:37]
	v_mad_i64_i32 v[112:113], s[6:7], v125, s46, v[112:113]
	v_lshl_add_u64 v[112:113], v[126:127], 1, v[112:113]
	global_store_dwordx2 v[112:113], v[114:115], off
.LBB0_121:
	s_or_b64 exec, exec, s[0:1]
	v_cmp_eq_u32_e64 s[42:43], 0, v129
	v_cndmask_b32_e32 v115, v173, v194, vcc
	v_cndmask_b32_e32 v114, v172, v190, vcc
	v_cndmask_b32_e64 v113, v195, v175, s[42:43]
	v_cndmask_b32_e64 v112, v191, v174, s[42:43]
	s_waitcnt vmcnt(4)
	v_pk_fma_f32 v[114:115], v[90:91], v[114:115], v[102:103]
	v_cndmask_b32_e32 v119, v159, v183, vcc
	v_cndmask_b32_e32 v118, v158, v178, vcc
	v_pk_fma_f32 v[112:113], v[94:95], v[112:113], v[114:115]
	v_cndmask_b32_e64 v117, v185, v171, s[42:43]
	v_cndmask_b32_e64 v116, v179, v170, s[42:43]
	v_pk_fma_f32 v[118:119], v[92:93], v[118:119], v[104:105]
	v_pk_fma_f32 v[112:113], v[132:133], v[98:99], v[112:113]
	v_pk_fma_f32 v[116:117], v[96:97], v[116:117], v[118:119]
	v_cndmask_b32_e32 v133, v194, v187, vcc
	v_cndmask_b32_e32 v132, v190, v181, vcc
	v_pk_fma_f32 v[116:117], v[130:131], v[100:101], v[116:117]
	v_cndmask_b32_e64 v131, v189, v195, s[42:43]
	v_cndmask_b32_e64 v130, v184, v191, s[42:43]
	v_pk_fma_f32 v[132:133], v[90:91], v[132:133], v[102:103]
	v_cndmask_b32_e32 v159, v183, v176, vcc
	v_pk_fma_f32 v[130:131], v[94:95], v[130:131], v[132:133]
	v_cndmask_b32_e32 v158, v178, v0, vcc
	v_pk_fma_f32 v[130:131], v[156:157], v[98:99], v[130:131]
	v_cndmask_b32_e64 v157, v177, v185, s[42:43]
	v_cndmask_b32_e64 v156, v107, v179, s[42:43]
	v_pk_fma_f32 v[158:159], v[92:93], v[158:159], v[104:105]
	v_cndmask_b32_e32 v171, v187, v196, vcc
	v_cndmask_b32_e32 v170, v181, v192, vcc
	v_pk_fma_f32 v[156:157], v[96:97], v[156:157], v[158:159]
	v_cndmask_b32_e64 v159, v197, v189, s[42:43]
	v_cndmask_b32_e64 v158, v193, v184, s[42:43]
	v_pk_fma_f32 v[90:91], v[90:91], v[170:171], v[102:103]
	v_cndmask_b32_e32 v103, v176, v186, vcc
	v_pk_fma_f32 v[90:91], v[94:95], v[158:159], v[90:91]
	v_cndmask_b32_e32 v102, v0, v180, vcc
	v_pk_fma_f32 v[90:91], v[122:123], v[98:99], v[90:91]
	v_cndmask_b32_e64 v99, v188, v177, s[42:43]
	v_cndmask_b32_e64 v98, v182, v107, s[42:43]
	v_pk_fma_f32 v[92:93], v[92:93], v[102:103], v[104:105]
	v_pk_fma_f32 v[92:93], v[96:97], v[98:99], v[92:93]
	v_mov_b32_e32 v125, v124
	v_pk_fma_f32 v[92:93], v[120:121], v[100:101], v[92:93]
	v_mov_b32_e32 v129, v128
	v_mov_b32_e32 v98, v124
	v_mov_b32_e32 v99, v124
	v_pk_mul_f32 v[72:73], v[72:73], v[98:99]
	v_pk_mul_f32 v[70:71], v[70:71], v[124:125]
	v_pk_mul_f32 v[66:67], v[66:67], v[128:129]
	s_nop 1
	v_mov_b32_e32 v98, v128
	v_mov_b32_e32 v99, v128
	v_mov_b32_dpp v123, v70 row_ror:2 row_mask:0xf bank_mask:0xf
	v_mov_b32_dpp v125, v71 row_ror:2 row_mask:0xf bank_mask:0xf
	v_mov_b32_dpp v129, v72 row_ror:2 row_mask:0xf bank_mask:0xf
	v_mov_b32_dpp v159, v73 row_ror:2 row_mask:0xf bank_mask:0xf
	v_pk_fma_f32 v[134:135], v[134:135], v[100:101], v[156:157]
	v_pk_mul_f32 v[68:69], v[68:69], v[98:99]
	v_mov_b32_dpp v122, v70 row_ror:1 row_mask:0xf bank_mask:0xf
	v_mov_b32_dpp v124, v71 row_ror:1 row_mask:0xf bank_mask:0xf
	v_mov_b32_dpp v128, v72 row_ror:1 row_mask:0xf bank_mask:0xf
	v_mov_b32_dpp v158, v73 row_ror:1 row_mask:0xf bank_mask:0xf
	v_cndmask_b32_e32 v98, v152, v123, vcc
	v_cndmask_b32_e32 v99, v153, v125, vcc
	v_cndmask_b32_e32 v100, v154, v129, vcc
	v_cndmask_b32_e32 v101, v155, v159, vcc
	v_cndmask_b32_e64 v102, v122, v136, s[42:43]
	v_cndmask_b32_e64 v103, v124, v137, s[42:43]
	v_cndmask_b32_e64 v104, v128, v150, s[42:43]
	v_cndmask_b32_e64 v105, v158, v151, s[42:43]
	s_waitcnt vmcnt(1)
	v_pk_fma_f32 v[100:101], v[84:85], v[100:101], v[88:89]
	v_pk_fma_f32 v[98:99], v[82:83], v[98:99], v[86:87]
	v_pk_fma_f32 v[100:101], v[80:81], v[104:105], v[100:101]
	v_pk_fma_f32 v[98:99], v[78:79], v[102:103], v[98:99]
	v_add_u32_e32 v0, 0x90, v106
	v_add_u32_e32 v120, 0xa0, v106
	v_add_u32_e32 v121, 0xb0, v106
	v_pk_mul_f32 v[114:115], v[112:113], s[98:99] op_sel_hi:[1,0]
	v_pk_mul_f32 v[118:119], v[116:117], s[98:99] op_sel_hi:[1,0]
	v_exp_f32_e32 v114, v114
	v_exp_f32_e32 v115, v115
	v_exp_f32_e32 v118, v118
	v_exp_f32_e32 v119, v119
	v_pk_add_f32 v[114:115], v[114:115], 1.0 op_sel_hi:[1,0]
	v_pk_add_f32 v[118:119], v[118:119], 1.0 op_sel_hi:[1,0]
	v_rcp_f32_e32 v114, v114
	v_rcp_f32_e32 v115, v115
	v_rcp_f32_e32 v118, v118
	v_rcp_f32_e32 v119, v119
	v_pk_mul_f32 v[106:107], v[112:113], v[114:115]
	v_pk_mul_f32 v[112:113], v[116:117], v[118:119]
	v_pk_fma_f32 v[72:73], v[72:73], v[76:77], v[100:101]
	v_pk_fma_f32 v[70:71], v[70:71], v[74:75], v[98:99]
	v_pk_mul_f32 v[72:73], v[112:113], v[72:73]
	v_pk_mul_f32 v[70:71], v[106:107], v[70:71]
	v_cvt_pk_bf16_f32 v70, v70, v71
	v_cvt_pk_bf16_f32 v71, v72, v73
	v_mov_b64_e32 v[72:73], s[36:37]
	v_mad_i64_i32 v[98:99], s[0:1], v0, s46, v[72:73]
	v_lshlrev_b64 v[100:101], 1, v[126:127]
	s_nop 1
	v_lshl_add_u64 v[98:99], v[98:99], 0, v[100:101]
	v_mov_b32_dpp v114, v66 row_ror:2 row_mask:0xf bank_mask:0xf
	v_mov_b32_dpp v116, v67 row_ror:2 row_mask:0xf bank_mask:0xf
	v_mov_b32_dpp v118, v68 row_ror:2 row_mask:0xf bank_mask:0xf
	v_mov_b32_dpp v126, v69 row_ror:2 row_mask:0xf bank_mask:0xf
	global_store_dwordx2 v[98:99], v[70:71], off
	v_mov_b32_dpp v0, v66 row_ror:1 row_mask:0xf bank_mask:0xf
	v_mov_b32_dpp v115, v67 row_ror:1 row_mask:0xf bank_mask:0xf
	v_mov_b32_dpp v117, v68 row_ror:1 row_mask:0xf bank_mask:0xf
	v_mov_b32_dpp v119, v69 row_ror:1 row_mask:0xf bank_mask:0xf
	v_cndmask_b32_e32 v70, v123, v114, vcc
	v_cndmask_b32_e32 v71, v125, v116, vcc
	v_cndmask_b32_e32 v98, v129, v118, vcc
	v_cndmask_b32_e32 v99, v159, v126, vcc
	v_cndmask_b32_e64 v102, v0, v122, s[42:43]
	v_cndmask_b32_e64 v103, v115, v124, s[42:43]
	v_cndmask_b32_e64 v104, v117, v128, s[42:43]
	v_cndmask_b32_e64 v105, v119, v158, s[42:43]
	v_pk_fma_f32 v[98:99], v[84:85], v[98:99], v[88:89]
	v_pk_fma_f32 v[70:71], v[82:83], v[70:71], v[86:87]
	v_pk_fma_f32 v[98:99], v[80:81], v[104:105], v[98:99]
	v_pk_fma_f32 v[70:71], v[78:79], v[102:103], v[70:71]
	v_pk_mul_f32 v[132:133], v[130:131], s[98:99] op_sel_hi:[1,0]
	v_pk_mul_f32 v[156:157], v[134:135], s[98:99] op_sel_hi:[1,0]
	v_exp_f32_e32 v132, v132
	v_exp_f32_e32 v133, v133
	v_exp_f32_e32 v156, v156
	v_exp_f32_e32 v157, v157
	v_pk_add_f32 v[132:133], v[132:133], 1.0 op_sel_hi:[1,0]
	v_pk_add_f32 v[156:157], v[156:157], 1.0 op_sel_hi:[1,0]
	v_rcp_f32_e32 v132, v132
	v_rcp_f32_e32 v133, v133
	v_rcp_f32_e32 v156, v156
	v_rcp_f32_e32 v157, v157
	v_pk_mul_f32 v[106:107], v[130:131], v[132:133]
	v_pk_mul_f32 v[112:113], v[134:135], v[156:157]
	v_pk_fma_f32 v[68:69], v[68:69], v[76:77], v[98:99]
	v_pk_fma_f32 v[66:67], v[66:67], v[74:75], v[70:71]
	v_pk_mul_f32 v[68:69], v[112:113], v[68:69]
	v_pk_mul_f32 v[66:67], v[106:107], v[66:67]
	v_cvt_pk_bf16_f32 v66, v66, v67
	v_cvt_pk_bf16_f32 v67, v68, v69
	v_mad_i64_i32 v[68:69], s[0:1], v120, s46, v[72:73]
	v_lshl_add_u64 v[68:69], v[68:69], 0, v[100:101]
	global_store_dwordx2 v[68:69], v[66:67], off
	s_nop 1
	v_mov_b32_dpp v66, v110 row_ror:2 row_mask:0xf bank_mask:0xf
	v_mov_b32_dpp v67, v111 row_ror:2 row_mask:0xf bank_mask:0xf
	v_mov_b32_dpp v68, v108 row_ror:2 row_mask:0xf bank_mask:0xf
	v_mov_b32_dpp v69, v109 row_ror:2 row_mask:0xf bank_mask:0xf
	v_mov_b32_dpp v70, v110 row_ror:1 row_mask:0xf bank_mask:0xf
	v_mov_b32_dpp v71, v111 row_ror:1 row_mask:0xf bank_mask:0xf
	v_mov_b32_dpp v98, v108 row_ror:1 row_mask:0xf bank_mask:0xf
	v_mov_b32_dpp v99, v109 row_ror:1 row_mask:0xf bank_mask:0xf
	v_cndmask_b32_e32 v66, v114, v66, vcc
	v_cndmask_b32_e32 v67, v116, v67, vcc
	v_cndmask_b32_e32 v68, v118, v68, vcc
	v_cndmask_b32_e32 v69, v126, v69, vcc
	v_cndmask_b32_e64 v70, v70, v0, s[42:43]
	v_cndmask_b32_e64 v71, v71, v115, s[42:43]
	v_cndmask_b32_e64 v98, v98, v117, s[42:43]
	v_cndmask_b32_e64 v99, v99, v119, s[42:43]
	v_pk_fma_f32 v[66:67], v[82:83], v[66:67], v[86:87]
	v_pk_fma_f32 v[68:69], v[84:85], v[68:69], v[88:89]
	v_pk_fma_f32 v[66:67], v[78:79], v[70:71], v[66:67]
	v_pk_fma_f32 v[68:69], v[80:81], v[98:99], v[68:69]
	v_pk_mul_f32 v[94:95], v[90:91], s[98:99] op_sel_hi:[1,0]
	v_pk_mul_f32 v[96:97], v[92:93], s[98:99] op_sel_hi:[1,0]
	v_exp_f32_e32 v94, v94
	v_exp_f32_e32 v95, v95
	v_exp_f32_e32 v96, v96
	v_exp_f32_e32 v97, v97
	v_pk_add_f32 v[94:95], v[94:95], 1.0 op_sel_hi:[1,0]
	v_pk_add_f32 v[96:97], v[96:97], 1.0 op_sel_hi:[1,0]
	v_rcp_f32_e32 v94, v94
	v_rcp_f32_e32 v95, v95
	v_rcp_f32_e32 v96, v96
	v_rcp_f32_e32 v97, v97
	v_pk_mul_f32 v[90:91], v[90:91], v[94:95]
	v_pk_mul_f32 v[92:93], v[92:93], v[96:97]
	v_pk_fma_f32 v[66:67], v[110:111], v[74:75], v[66:67]
	v_pk_fma_f32 v[68:69], v[108:109], v[76:77], v[68:69]
	v_pk_mul_f32 v[66:67], v[90:91], v[66:67]
	v_pk_mul_f32 v[68:69], v[92:93], v[68:69]
	v_cvt_pk_bf16_f32 v66, v66, v67
	s_nop 0
	v_cvt_pk_bf16_f32 v67, v68, v69
	v_mad_i64_i32 v[68:69], s[0:1], v121, s46, v[72:73]
	v_lshl_add_u64 v[68:69], v[68:69], 0, v[100:101]
	global_store_dwordx2 v[68:69], v[66:67], off
	s_nop 0
	v_and_b32_e32 v97, 15, v226
	v_or_b32_e32 v74, s4, v97
	v_ashrrev_i32_e32 v75, 31, v74
	v_lshl_add_u64 v[72:73], v[74:75], 3, s[38:39]
	global_load_dwordx2 v[76:77], v[72:73], off
	global_load_dwordx2 v[70:71], v[72:73], off offset:128
	global_load_dwordx2 v[68:69], v[72:73], off offset:256
	s_nop 0
	global_load_dwordx2 v[72:73], v[72:73], off offset:384
	v_ashrrev_i32_e32 v0, 1, v226
	v_and_b32_e32 v0, -8, v0
	v_add_u32_e32 v66, s21, v0
	s_waitcnt vmcnt(3)
	v_ffbh_u32_e32 v0, v77
	v_min_u32_e32 v0, 32, v0
	v_lshlrev_b64 v[76:77], v0, v[76:77]
	v_min_u32_e32 v67, 1, v76
	v_or_b32_e32 v67, v77, v67
	v_cvt_f32_u32_e32 v67, v67
	v_sub_u32_e32 v0, 32, v0
	v_ldexp_f32 v0, v67, v0
	v_fmamk_f32 v0, v0, 0x2e800000, v210
	s_nop 0
	v_rsq_f32_e32 v0, v0
	s_nop 0
	s_nop 0
	v_ashrrev_i32_e32 v67, 31, v66
	v_pk_mul_f32 v[92:93], v[64:65], v[0:1] op_sel_hi:[1,0]
	v_pk_mul_f32 v[90:91], v[62:63], v[0:1] op_sel_hi:[1,0]
	v_pk_mul_f32 v[86:87], v[60:61], v[0:1] op_sel_hi:[1,0]
	v_pk_mul_f32 v[88:89], v[58:59], v[0:1] op_sel_hi:[1,0]
	v_lshl_add_u64 v[58:59], v[66:67], 1, s[76:77]
	v_cmp_gt_u32_e32 vcc, 2, v97
	s_and_saveexec_b64 s[0:1], vcc
	s_cbranch_execz .LBB0_123
	v_mul_u32_u24_e32 v0, 0x1600, v97
	v_lshlrev_b32_e32 v0, 1, v0
	v_cvt_pk_bf16_f32 v60, v90, v91
	v_cvt_pk_bf16_f32 v61, v92, v93
	v_lshl_add_u64 v[64:65], v[58:59], 0, v[0:1]
	v_cvt_pk_bf16_f32 v62, v88, v89
	v_cvt_pk_bf16_f32 v63, v86, v87
	global_store_dwordx2 v[64:65], v[60:61], off offset:8
	global_store_dwordx2 v[64:65], v[62:63], off offset:264

.LBB0_125:
	s_or_b64 exec, exec, s[0:1]
	v_ffbh_u32_e32 v0, v71
	v_min_u32_e32 v0, 32, v0
	v_lshlrev_b64 v[50:51], v0, v[70:71]
	v_min_u32_e32 v50, 1, v50
	v_or_b32_e32 v50, v51, v50
	v_cvt_f32_u32_e32 v50, v50
	v_sub_u32_e32 v0, 32, v0
	s_or_b32 s5, s5, 4
	v_add_u32_e32 v94, s5, v66
	v_ldexp_f32 v0, v50, v0
	v_fmamk_f32 v0, v0, 0x2e800000, v210
	s_nop 0
	v_rsq_f32_e32 v0, v0
	s_nop 0
	s_nop 0
	v_mov_b32_e32 v84, v0
	v_ffbh_u32_e32 v0, v69
	v_min_u32_e32 v0, 32, v0
	v_pk_mul_f32 v[100:101], v[46:47], v[84:85] op_sel_hi:[1,0]
	v_lshlrev_b64 v[46:47], v0, v[68:69]
	v_min_u32_e32 v46, 1, v46
	v_or_b32_e32 v46, v47, v46
	v_cvt_f32_u32_e32 v46, v46
	v_sub_u32_e32 v0, 32, v0
	v_pk_mul_f32 v[98:99], v[48:49], v[84:85] op_sel_hi:[1,0]
	v_ldexp_f32 v0, v46, v0
	v_fmamk_f32 v0, v0, 0x2e800000, v210
	s_nop 0
	v_rsq_f32_e32 v0, v0
	s_nop 0
	s_nop 0
	v_mov_b32_e32 v96, v0
	v_pk_mul_f32 v[102:103], v[44:45], v[96:97] op_sel_hi:[1,0]
	v_pk_mul_f32 v[112:113], v[42:43], v[96:97] op_sel_hi:[1,0]
	v_ashrrev_i32_e32 v95, 31, v94
	v_lshlrev_b64 v[54:55], 2, v[94:95]
	v_lshl_add_u64 v[42:43], s[44:45], 0, v[54:55]
	v_lshl_add_u64 v[44:45], s[60:61], 0, v[54:55]
	global_load_dwordx4 v[58:61], v[42:43], off
	global_load_dwordx4 v[62:65], v[44:45], off
	v_lshl_add_u64 v[42:43], s[2:3], 0, v[54:55]
	global_load_dwordx4 v[66:69], v[42:43], off
	v_lshl_add_u64 v[42:43], s[48:49], 0, v[54:55]
	global_load_dwordx4 v[70:73], v[42:43], off
	s_nop 1
	v_cmp_lt_u32_e32 vcc, 1, v97
	v_mov_b32_dpp v120, v90 row_ror:1 row_mask:0xf bank_mask:0xf
	v_mov_b32_dpp v118, v90 row_ror:2 row_mask:0xf bank_mask:0xf
	v_mov_b32_dpp v121, v91 row_ror:1 row_mask:0xf bank_mask:0xf
	v_mov_b32_dpp v119, v91 row_ror:2 row_mask:0xf bank_mask:0xf
	v_mov_b32_dpp v116, v92 row_ror:1 row_mask:0xf bank_mask:0xf
	v_mov_b32_dpp v114, v92 row_ror:2 row_mask:0xf bank_mask:0xf
	v_mov_b32_dpp v117, v93 row_ror:1 row_mask:0xf bank_mask:0xf
	v_mov_b32_dpp v115, v93 row_ror:2 row_mask:0xf bank_mask:0xf
	v_mov_b32_dpp v137, v100 row_ror:1 row_mask:0xf bank_mask:0xf
	v_mov_b32_dpp v136, v100 row_ror:2 row_mask:0xf bank_mask:0xf
	v_mov_b32_dpp v153, v101 row_ror:1 row_mask:0xf bank_mask:0xf
	v_mov_b32_dpp v152, v101 row_ror:2 row_mask:0xf bank_mask:0xf
	v_mov_b32_dpp v125, v98 row_ror:1 row_mask:0xf bank_mask:0xf
	v_mov_b32_dpp v124, v98 row_ror:2 row_mask:0xf bank_mask:0xf
	v_mov_b32_dpp v131, v99 row_ror:1 row_mask:0xf bank_mask:0xf
	v_mov_b32_dpp v129, v99 row_ror:2 row_mask:0xf bank_mask:0xf
	v_mov_b32_dpp v130, v112 row_ror:1 row_mask:0xf bank_mask:0xf
	v_mov_b32_dpp v127, v112 row_ror:2 row_mask:0xf bank_mask:0xf
	v_mov_b32_dpp v135, v113 row_ror:1 row_mask:0xf bank_mask:0xf
	v_mov_b32_dpp v133, v113 row_ror:2 row_mask:0xf bank_mask:0xf
	v_mov_b32_dpp v75, v102 row_ror:1 row_mask:0xf bank_mask:0xf
	v_mov_b32_dpp v0, v102 row_ror:2 row_mask:0xf bank_mask:0xf
	v_mov_b32_dpp v123, v103 row_ror:1 row_mask:0xf bank_mask:0xf
	v_mov_b32_dpp v122, v103 row_ror:2 row_mask:0xf bank_mask:0xf
	v_mov_b32_dpp v151, v82 row_ror:1 row_mask:0xf bank_mask:0xf
	v_mov_b32_dpp v150, v82 row_ror:2 row_mask:0xf bank_mask:0xf
	v_mov_b32_dpp v155, v83 row_ror:1 row_mask:0xf bank_mask:0xf
	v_mov_b32_dpp v154, v83 row_ror:2 row_mask:0xf bank_mask:0xf
	v_mov_b32_dpp v128, v80 row_ror:1 row_mask:0xf bank_mask:0xf
	v_mov_b32_dpp v126, v80 row_ror:2 row_mask:0xf bank_mask:0xf
	v_mov_b32_dpp v134, v81 row_ror:1 row_mask:0xf bank_mask:0xf
	v_mov_b32_dpp v132, v81 row_ror:2 row_mask:0xf bank_mask:0xf
	v_lshl_add_u64 v[42:43], s[96:97], 0, v[54:55]
	v_lshl_add_u64 v[44:45], s[62:63], 0, v[54:55]
	global_load_dwordx4 v[50:53], v[42:43], off
	global_load_dwordx4 v[46:49], v[44:45], off
	v_lshl_add_u64 v[42:43], s[64:65], 0, v[54:55]
	v_lshl_add_u64 v[54:55], s[66:67], 0, v[54:55]
	global_load_dwordx4 v[42:45], v[42:43], off
	s_nop 1
	global_load_dwordx4 v[54:57], v[54:55], off
	v_mov_b32_dpp v104, v88 row_ror:1 row_mask:0xf bank_mask:0xf
	v_mov_b32_dpp v108, v88 row_ror:2 row_mask:0xf bank_mask:0xf
	v_mov_b32_dpp v105, v89 row_ror:1 row_mask:0xf bank_mask:0xf
	v_mov_b32_dpp v109, v89 row_ror:2 row_mask:0xf bank_mask:0xf
	v_mov_b32_dpp v106, v86 row_ror:1 row_mask:0xf bank_mask:0xf
	v_mov_b32_dpp v110, v86 row_ror:2 row_mask:0xf bank_mask:0xf
	v_mov_b32_dpp v107, v87 row_ror:1 row_mask:0xf bank_mask:0xf
	v_mov_b32_dpp v111, v87 row_ror:2 row_mask:0xf bank_mask:0xf
	s_and_saveexec_b64 s[0:1], vcc
	s_cbranch_execz .Lcg_skip2
	s_waitcnt vmcnt(4)
	v_pk_fma_f32 v[156:157], v[60:61], v[114:115], v[72:73]
	s_nop 0
	v_pk_fma_f32 v[156:157], v[64:65], v[116:117], v[156:157]
	s_nop 0
	v_pk_fma_f32 v[92:93], v[92:93], v[68:69], v[156:157]
	v_pk_fma_f32 v[156:157], v[58:59], v[118:119], v[70:71]
	v_pk_fma_f32 v[156:157], v[62:63], v[120:121], v[156:157]
	v_pk_fma_f32 v[90:91], v[90:91], v[66:67], v[156:157]
	v_pk_mul_f32 v[156:157], v[90:91], s[98:99] op_sel_hi:[1,0]
	v_pk_mul_f32 v[158:159], v[92:93], s[98:99] op_sel_hi:[1,0]
	v_exp_f32_e32 v156, v156
	v_exp_f32_e32 v157, v157
	v_exp_f32_e32 v158, v158
	v_exp_f32_e32 v159, v159
	v_pk_add_f32 v[156:157], v[156:157], 1.0 op_sel_hi:[1,0]
	v_pk_add_f32 v[158:159], v[158:159], 1.0 op_sel_hi:[1,0]
	v_rcp_f32_e32 v156, v156
	v_rcp_f32_e32 v157, v157
	v_rcp_f32_e32 v158, v158
	v_rcp_f32_e32 v159, v159
	v_pk_mul_f32 v[90:91], v[90:91], v[156:157]
	v_pk_mul_f32 v[92:93], v[92:93], v[158:159]
	s_waitcnt vmcnt(0)
	v_pk_fma_f32 v[156:157], v[52:53], v[110:111], v[56:57]
	v_pk_fma_f32 v[158:159], v[50:51], v[108:109], v[54:55]
	v_pk_fma_f32 v[156:157], v[48:49], v[106:107], v[156:157]
	v_pk_fma_f32 v[158:159], v[46:47], v[104:105], v[158:159]
	v_pk_fma_f32 v[86:87], v[86:87], v[44:45], v[156:157]
	v_pk_fma_f32 v[88:89], v[88:89], v[42:43], v[158:159]
	v_pk_mul_f32 v[86:87], v[92:93], v[86:87]
	v_pk_mul_f32 v[88:89], v[90:91], v[88:89]
	s_nop 0
	v_cvt_pk_bf16_f32 v88, v88, v89
	v_cvt_pk_bf16_f32 v89, v86, v87
	v_mov_b64_e32 v[86:87], s[36:37]
	v_mad_i64_i32 v[86:87], s[6:7], v74, s46, v[86:87]
	v_lshl_add_u64 v[86:87], v[94:95], 1, v[86:87]
	global_store_dwordx2 v[86:87], v[88:89], off
.LBB0_127:
	s_or_b64 exec, exec, s[0:1]
	v_cmp_eq_u32_e64 s[42:43], 0, v97
	v_cndmask_b32_e32 v89, v119, v152, vcc
	v_cndmask_b32_e32 v88, v118, v136, vcc
	v_cndmask_b32_e64 v87, v153, v121, s[42:43]
	v_cndmask_b32_e64 v86, v137, v120, s[42:43]
	s_waitcnt vmcnt(4)
	v_pk_fma_f32 v[88:89], v[58:59], v[88:89], v[70:71]
	v_cndmask_b32_e32 v93, v115, v129, vcc
	v_cndmask_b32_e32 v92, v114, v124, vcc
	v_pk_fma_f32 v[86:87], v[62:63], v[86:87], v[88:89]
	v_cndmask_b32_e64 v91, v131, v117, s[42:43]
	v_cndmask_b32_e64 v90, v125, v116, s[42:43]
	v_pk_fma_f32 v[92:93], v[60:61], v[92:93], v[72:73]
	v_pk_fma_f32 v[86:87], v[100:101], v[66:67], v[86:87]
	v_pk_fma_f32 v[90:91], v[64:65], v[90:91], v[92:93]
	v_cndmask_b32_e32 v101, v152, v133, vcc
	v_cndmask_b32_e32 v100, v136, v127, vcc
	v_pk_fma_f32 v[90:91], v[98:99], v[68:69], v[90:91]
	v_cndmask_b32_e64 v99, v135, v153, s[42:43]
	v_cndmask_b32_e64 v98, v130, v137, s[42:43]
	v_pk_fma_f32 v[100:101], v[58:59], v[100:101], v[70:71]
	v_cndmask_b32_e32 v115, v129, v122, vcc
	v_pk_fma_f32 v[98:99], v[62:63], v[98:99], v[100:101]
	v_cndmask_b32_e32 v114, v124, v0, vcc
	v_pk_fma_f32 v[98:99], v[112:113], v[66:67], v[98:99]
	v_cndmask_b32_e64 v113, v123, v131, s[42:43]
	v_cndmask_b32_e64 v112, v75, v125, s[42:43]
	v_pk_fma_f32 v[114:115], v[60:61], v[114:115], v[72:73]
	v_cndmask_b32_e32 v117, v133, v154, vcc
	v_cndmask_b32_e32 v116, v127, v150, vcc
	v_pk_fma_f32 v[112:113], v[64:65], v[112:113], v[114:115]
	v_cndmask_b32_e64 v115, v155, v135, s[42:43]
	v_cndmask_b32_e64 v114, v151, v130, s[42:43]
	v_pk_fma_f32 v[58:59], v[58:59], v[116:117], v[70:71]
	v_cndmask_b32_e32 v71, v122, v132, vcc
	v_pk_fma_f32 v[58:59], v[62:63], v[114:115], v[58:59]
	v_cndmask_b32_e32 v70, v0, v126, vcc
	v_pk_fma_f32 v[58:59], v[82:83], v[66:67], v[58:59]
	v_cndmask_b32_e64 v67, v134, v123, s[42:43]
	v_cndmask_b32_e64 v66, v128, v75, s[42:43]
	v_pk_fma_f32 v[60:61], v[60:61], v[70:71], v[72:73]
	v_pk_fma_f32 v[60:61], v[64:65], v[66:67], v[60:61]
	v_mov_b32_e32 v85, v84
	v_pk_fma_f32 v[60:61], v[80:81], v[68:69], v[60:61]
	v_mov_b32_e32 v97, v96
	v_mov_b32_e32 v66, v84
	v_mov_b32_e32 v67, v84
	v_pk_mul_f32 v[40:41], v[40:41], v[66:67]
	v_pk_mul_f32 v[38:39], v[38:39], v[84:85]
	v_pk_mul_f32 v[34:35], v[34:35], v[96:97]
	s_nop 1
	v_mov_b32_e32 v66, v96
	v_mov_b32_e32 v67, v96
	v_mov_b32_dpp v85, v38 row_ror:2 row_mask:0xf bank_mask:0xf
	v_mov_b32_dpp v97, v39 row_ror:2 row_mask:0xf bank_mask:0xf
	v_mov_b32_dpp v115, v40 row_ror:2 row_mask:0xf bank_mask:0xf
	v_mov_b32_dpp v117, v41 row_ror:2 row_mask:0xf bank_mask:0xf
	v_pk_fma_f32 v[102:103], v[102:103], v[68:69], v[112:113]
	v_pk_mul_f32 v[36:37], v[36:37], v[66:67]
	v_mov_b32_dpp v84, v38 row_ror:1 row_mask:0xf bank_mask:0xf
	v_mov_b32_dpp v96, v39 row_ror:1 row_mask:0xf bank_mask:0xf
	v_mov_b32_dpp v114, v40 row_ror:1 row_mask:0xf bank_mask:0xf
	v_mov_b32_dpp v116, v41 row_ror:1 row_mask:0xf bank_mask:0xf
	v_cndmask_b32_e32 v66, v108, v85, vcc
	v_cndmask_b32_e32 v67, v109, v97, vcc
	v_cndmask_b32_e32 v68, v110, v115, vcc
	v_cndmask_b32_e32 v69, v111, v117, vcc
	v_cndmask_b32_e64 v70, v84, v104, s[42:43]
	v_cndmask_b32_e64 v71, v96, v105, s[42:43]
	v_cndmask_b32_e64 v72, v114, v106, s[42:43]
	v_cndmask_b32_e64 v73, v116, v107, s[42:43]
	s_waitcnt vmcnt(1)
	v_pk_fma_f32 v[68:69], v[52:53], v[68:69], v[56:57]
	v_pk_fma_f32 v[66:67], v[50:51], v[66:67], v[54:55]
	v_pk_fma_f32 v[68:69], v[48:49], v[72:73], v[68:69]
	v_pk_fma_f32 v[66:67], v[46:47], v[70:71], v[66:67]
	v_or_b32_e32 v0, 16, v74
	v_or_b32_e32 v82, 32, v74
	v_or_b32_e32 v83, 48, v74
	v_pk_mul_f32 v[88:89], v[86:87], s[98:99] op_sel_hi:[1,0]
	v_pk_mul_f32 v[92:93], v[90:91], s[98:99] op_sel_hi:[1,0]
	v_exp_f32_e32 v88, v88
	v_exp_f32_e32 v89, v89
	v_exp_f32_e32 v92, v92
	v_exp_f32_e32 v93, v93
	v_pk_add_f32 v[88:89], v[88:89], 1.0 op_sel_hi:[1,0]
	v_pk_add_f32 v[92:93], v[92:93], 1.0 op_sel_hi:[1,0]
	v_rcp_f32_e32 v88, v88
	v_rcp_f32_e32 v89, v89
	v_rcp_f32_e32 v92, v92
	v_rcp_f32_e32 v93, v93
	v_pk_mul_f32 v[74:75], v[86:87], v[88:89]
	v_pk_mul_f32 v[80:81], v[90:91], v[92:93]
	v_pk_fma_f32 v[40:41], v[40:41], v[44:45], v[68:69]
	v_pk_fma_f32 v[38:39], v[38:39], v[42:43], v[66:67]
	v_pk_mul_f32 v[40:41], v[80:81], v[40:41]
	v_pk_mul_f32 v[38:39], v[74:75], v[38:39]
	v_cvt_pk_bf16_f32 v38, v38, v39
	v_cvt_pk_bf16_f32 v39, v40, v41
	v_mov_b64_e32 v[40:41], s[36:37]
	v_mad_i64_i32 v[66:67], s[0:1], v0, s46, v[40:41]
	v_lshlrev_b64 v[68:69], 1, v[94:95]
	s_nop 1
	v_lshl_add_u64 v[66:67], v[66:67], 0, v[68:69]
	v_mov_b32_dpp v86, v34 row_ror:2 row_mask:0xf bank_mask:0xf
	v_mov_b32_dpp v88, v35 row_ror:2 row_mask:0xf bank_mask:0xf
	v_mov_b32_dpp v90, v36 row_ror:2 row_mask:0xf bank_mask:0xf
	v_mov_b32_dpp v92, v37 row_ror:2 row_mask:0xf bank_mask:0xf
	global_store_dwordx2 v[66:67], v[38:39], off
	v_mov_b32_dpp v0, v34 row_ror:1 row_mask:0xf bank_mask:0xf
	v_mov_b32_dpp v87, v35 row_ror:1 row_mask:0xf bank_mask:0xf
	v_mov_b32_dpp v89, v36 row_ror:1 row_mask:0xf bank_mask:0xf
	v_mov_b32_dpp v91, v37 row_ror:1 row_mask:0xf bank_mask:0xf
	v_cndmask_b32_e32 v38, v85, v86, vcc
	v_cndmask_b32_e32 v39, v97, v88, vcc
	v_cndmask_b32_e32 v66, v115, v90, vcc
	v_cndmask_b32_e32 v67, v117, v92, vcc
	v_cndmask_b32_e64 v70, v0, v84, s[42:43]
	v_cndmask_b32_e64 v71, v87, v96, s[42:43]
	v_cndmask_b32_e64 v72, v89, v114, s[42:43]
	v_cndmask_b32_e64 v73, v91, v116, s[42:43]
	v_pk_fma_f32 v[66:67], v[52:53], v[66:67], v[56:57]
	v_pk_fma_f32 v[38:39], v[50:51], v[38:39], v[54:55]
	v_pk_fma_f32 v[66:67], v[48:49], v[72:73], v[66:67]
	v_pk_fma_f32 v[38:39], v[46:47], v[70:71], v[38:39]
	v_pk_mul_f32 v[100:101], v[98:99], s[98:99] op_sel_hi:[1,0]
	v_pk_mul_f32 v[112:113], v[102:103], s[98:99] op_sel_hi:[1,0]
	v_exp_f32_e32 v100, v100
	v_exp_f32_e32 v101, v101
	v_exp_f32_e32 v112, v112
	v_exp_f32_e32 v113, v113
	v_pk_add_f32 v[100:101], v[100:101], 1.0 op_sel_hi:[1,0]
	v_pk_add_f32 v[112:113], v[112:113], 1.0 op_sel_hi:[1,0]
	v_rcp_f32_e32 v100, v100
	v_rcp_f32_e32 v101, v101
	v_rcp_f32_e32 v112, v112
	v_rcp_f32_e32 v113, v113
	v_pk_mul_f32 v[74:75], v[98:99], v[100:101]
	v_pk_mul_f32 v[80:81], v[102:103], v[112:113]
	v_pk_fma_f32 v[36:37], v[36:37], v[44:45], v[66:67]
	v_pk_fma_f32 v[34:35], v[34:35], v[42:43], v[38:39]
	v_pk_mul_f32 v[36:37], v[80:81], v[36:37]
	v_pk_mul_f32 v[34:35], v[74:75], v[34:35]
	v_cvt_pk_bf16_f32 v34, v34, v35
	v_cvt_pk_bf16_f32 v35, v36, v37
	v_mad_i64_i32 v[36:37], s[0:1], v82, s46, v[40:41]
	v_lshl_add_u64 v[36:37], v[36:37], 0, v[68:69]
	global_store_dwordx2 v[36:37], v[34:35], off
	s_nop 1
	v_mov_b32_dpp v34, v78 row_ror:2 row_mask:0xf bank_mask:0xf
	v_mov_b32_dpp v35, v79 row_ror:2 row_mask:0xf bank_mask:0xf
	v_mov_b32_dpp v36, v76 row_ror:2 row_mask:0xf bank_mask:0xf
	v_mov_b32_dpp v37, v77 row_ror:2 row_mask:0xf bank_mask:0xf
	v_mov_b32_dpp v38, v78 row_ror:1 row_mask:0xf bank_mask:0xf
	v_mov_b32_dpp v39, v79 row_ror:1 row_mask:0xf bank_mask:0xf
	v_mov_b32_dpp v66, v76 row_ror:1 row_mask:0xf bank_mask:0xf
	v_mov_b32_dpp v67, v77 row_ror:1 row_mask:0xf bank_mask:0xf
	v_cndmask_b32_e32 v34, v86, v34, vcc
	v_cndmask_b32_e32 v35, v88, v35, vcc
	v_cndmask_b32_e32 v36, v90, v36, vcc
	v_cndmask_b32_e32 v37, v92, v37, vcc
	v_cndmask_b32_e64 v38, v38, v0, s[42:43]
	v_cndmask_b32_e64 v39, v39, v87, s[42:43]
	v_cndmask_b32_e64 v66, v66, v89, s[42:43]
	v_cndmask_b32_e64 v67, v67, v91, s[42:43]
	v_pk_fma_f32 v[34:35], v[50:51], v[34:35], v[54:55]
	v_pk_fma_f32 v[36:37], v[52:53], v[36:37], v[56:57]
	v_pk_fma_f32 v[34:35], v[46:47], v[38:39], v[34:35]
	v_pk_fma_f32 v[36:37], v[48:49], v[66:67], v[36:37]
	v_pk_mul_f32 v[62:63], v[58:59], s[98:99] op_sel_hi:[1,0]
	v_pk_mul_f32 v[64:65], v[60:61], s[98:99] op_sel_hi:[1,0]
	v_exp_f32_e32 v62, v62
	v_exp_f32_e32 v63, v63
	v_exp_f32_e32 v64, v64
	v_exp_f32_e32 v65, v65
	v_pk_add_f32 v[62:63], v[62:63], 1.0 op_sel_hi:[1,0]
	v_pk_add_f32 v[64:65], v[64:65], 1.0 op_sel_hi:[1,0]
	v_rcp_f32_e32 v62, v62
	v_rcp_f32_e32 v63, v63
	v_rcp_f32_e32 v64, v64
	v_rcp_f32_e32 v65, v65
	v_pk_mul_f32 v[58:59], v[58:59], v[62:63]
	v_pk_mul_f32 v[60:61], v[60:61], v[64:65]
	v_pk_fma_f32 v[34:35], v[78:79], v[42:43], v[34:35]
	v_pk_fma_f32 v[36:37], v[76:77], v[44:45], v[36:37]
	v_pk_mul_f32 v[34:35], v[58:59], v[34:35]
	v_pk_mul_f32 v[36:37], v[60:61], v[36:37]
	v_cvt_pk_bf16_f32 v34, v34, v35
	s_nop 0
	v_cvt_pk_bf16_f32 v35, v36, v37
	v_mad_i64_i32 v[36:37], s[0:1], v83, s46, v[40:41]
	v_lshl_add_u64 v[36:37], v[36:37], 0, v[68:69]
	global_store_dwordx2 v[36:37], v[34:35], off
	s_nop 0
	v_and_b32_e32 v108, 15, v226
	v_or_b32_e32 v56, s4, v108
	v_ashrrev_i32_e32 v57, 31, v56
	v_lshl_add_u64 v[40:41], v[56:57], 3, s[38:39]
	global_load_dwordx2 v[42:43], v[40:41], off offset:1024
	global_load_dwordx2 v[38:39], v[40:41], off offset:1152
	global_load_dwordx2 v[36:37], v[40:41], off offset:1280
	s_nop 0
	global_load_dwordx2 v[40:41], v[40:41], off offset:1408
	v_ashrrev_i32_e32 v0, 1, v226
	v_and_b32_e32 v0, -8, v0
	v_add_u32_e32 v34, s21, v0
	s_waitcnt vmcnt(3)
	v_ffbh_u32_e32 v0, v43
	v_min_u32_e32 v0, 32, v0
	v_lshlrev_b64 v[42:43], v0, v[42:43]
	v_min_u32_e32 v35, 1, v42
	v_or_b32_e32 v35, v43, v35
	v_cvt_f32_u32_e32 v35, v35
	v_sub_u32_e32 v0, 32, v0
	v_ldexp_f32 v0, v35, v0
	v_fmamk_f32 v0, v0, 0x2e800000, v210
	s_nop 0
	v_rsq_f32_e32 v0, v0
	s_nop 0
	s_nop 0
	v_ashrrev_i32_e32 v35, 31, v34
	v_pk_mul_f32 v[84:85], v[32:33], v[0:1] op_sel_hi:[1,0]
	v_pk_mul_f32 v[44:45], v[30:31], v[0:1] op_sel_hi:[1,0]
	v_pk_mul_f32 v[72:73], v[28:29], v[0:1] op_sel_hi:[1,0]
	v_pk_mul_f32 v[42:43], v[26:27], v[0:1] op_sel_hi:[1,0]
	v_lshl_add_u64 v[26:27], v[34:35], 1, s[78:79]
	v_cmp_gt_u32_e32 vcc, 2, v108
	s_and_saveexec_b64 s[0:1], vcc
	s_cbranch_execz .LBB0_129
	v_mul_u32_u24_e32 v0, 0x1600, v108
	v_lshlrev_b32_e32 v0, 1, v0
	v_cvt_pk_bf16_f32 v28, v44, v45
	v_cvt_pk_bf16_f32 v29, v84, v85
	v_lshl_add_u64 v[32:33], v[26:27], 0, v[0:1]
	v_cvt_pk_bf16_f32 v30, v42, v43
	v_cvt_pk_bf16_f32 v31, v72, v73
	global_store_dwordx2 v[32:33], v[28:29], off offset:8
	global_store_dwordx2 v[32:33], v[30:31], off offset:264

.LBB0_131:
	s_or_b64 exec, exec, s[0:1]
	v_ffbh_u32_e32 v0, v39
	v_min_u32_e32 v0, 32, v0
	v_lshlrev_b64 v[14:15], v0, v[38:39]
	v_min_u32_e32 v14, 1, v14
	v_or_b32_e32 v14, v15, v14
	v_cvt_f32_u32_e32 v14, v14
	v_sub_u32_e32 v0, 32, v0
	v_add_u32_e32 v58, s5, v34
	v_ldexp_f32 v0, v14, v0
	v_fmamk_f32 v0, v0, 0x2e800000, v210
	s_nop 0
	v_rsq_f32_e32 v0, v0
	s_nop 0
	s_nop 0
	v_mov_b32_e32 v52, v0
	v_ffbh_u32_e32 v0, v37
	v_min_u32_e32 v0, 32, v0
	v_lshlrev_b64 v[14:15], v0, v[36:37]
	v_min_u32_e32 v14, 1, v14
	v_or_b32_e32 v14, v15, v14
	v_cvt_f32_u32_e32 v14, v14
	v_sub_u32_e32 v0, 32, v0
	v_pk_mul_f32 v[60:61], v[20:21], v[52:53] op_sel_hi:[1,0]
	v_pk_mul_f32 v[54:55], v[18:19], v[52:53] op_sel_hi:[1,0]
	v_ldexp_f32 v0, v14, v0
	v_fmamk_f32 v0, v0, 0x2e800000, v210
	s_nop 0
	v_rsq_f32_e32 v0, v0
	s_nop 0
	s_nop 0
	v_mov_b32_e32 v62, v0
	v_pk_mul_f32 v[88:89], v[12:13], v[62:63] op_sel_hi:[1,0]
	v_pk_mul_f32 v[82:83], v[10:11], v[62:63] op_sel_hi:[1,0]
	v_ashrrev_i32_e32 v59, 31, v58
	v_lshlrev_b64 v[22:23], 2, v[58:59]
	v_lshl_add_u64 v[10:11], s[44:45], 0, v[22:23]
	v_lshl_add_u64 v[12:13], s[60:61], 0, v[22:23]
	global_load_dwordx4 v[26:29], v[10:11], off
	global_load_dwordx4 v[30:33], v[12:13], off
	v_lshl_add_u64 v[10:11], s[2:3], 0, v[22:23]
	global_load_dwordx4 v[34:37], v[10:11], off
	v_lshl_add_u64 v[10:11], s[48:49], 0, v[22:23]
	global_load_dwordx4 v[38:41], v[10:11], off
	s_nop 1
	v_cmp_lt_u32_e32 vcc, 1, v108
	v_mov_b32_dpp v66, v44 row_ror:1 row_mask:0xf bank_mask:0xf
	v_mov_b32_dpp v87, v44 row_ror:2 row_mask:0xf bank_mask:0xf
	v_mov_b32_dpp v67, v45 row_ror:1 row_mask:0xf bank_mask:0xf
	v_mov_b32_dpp v86, v45 row_ror:2 row_mask:0xf bank_mask:0xf
	v_mov_b32_dpp v80, v84 row_ror:1 row_mask:0xf bank_mask:0xf
	v_mov_b32_dpp v91, v84 row_ror:2 row_mask:0xf bank_mask:0xf
	v_mov_b32_dpp v81, v85 row_ror:1 row_mask:0xf bank_mask:0xf
	v_mov_b32_dpp v90, v85 row_ror:2 row_mask:0xf bank_mask:0xf
	v_mov_b32_dpp v0, v54 row_ror:1 row_mask:0xf bank_mask:0xf
	v_mov_b32_dpp v97, v54 row_ror:2 row_mask:0xf bank_mask:0xf
	v_mov_b32_dpp v109, v55 row_ror:1 row_mask:0xf bank_mask:0xf
	v_mov_b32_dpp v96, v55 row_ror:2 row_mask:0xf bank_mask:0xf
	v_mov_b32_dpp v110, v60 row_ror:1 row_mask:0xf bank_mask:0xf
	v_mov_b32_dpp v99, v60 row_ror:2 row_mask:0xf bank_mask:0xf
	v_mov_b32_dpp v111, v61 row_ror:1 row_mask:0xf bank_mask:0xf
	v_mov_b32_dpp v98, v61 row_ror:2 row_mask:0xf bank_mask:0xf
	v_mov_b32_dpp v112, v82 row_ror:1 row_mask:0xf bank_mask:0xf
	v_mov_b32_dpp v93, v82 row_ror:2 row_mask:0xf bank_mask:0xf
	v_mov_b32_dpp v113, v83 row_ror:1 row_mask:0xf bank_mask:0xf
	v_mov_b32_dpp v92, v83 row_ror:2 row_mask:0xf bank_mask:0xf
	v_mov_b32_dpp v114, v88 row_ror:1 row_mask:0xf bank_mask:0xf
	v_mov_b32_dpp v95, v88 row_ror:2 row_mask:0xf bank_mask:0xf
	v_mov_b32_dpp v115, v89 row_ror:1 row_mask:0xf bank_mask:0xf
	v_mov_b32_dpp v94, v89 row_ror:2 row_mask:0xf bank_mask:0xf
	v_mov_b32_dpp v57, v64 row_ror:1 row_mask:0xf bank_mask:0xf
	v_mov_b32_dpp v101, v64 row_ror:2 row_mask:0xf bank_mask:0xf
	v_mov_b32_dpp v116, v65 row_ror:1 row_mask:0xf bank_mask:0xf
	v_mov_b32_dpp v100, v65 row_ror:2 row_mask:0xf bank_mask:0xf
	v_mov_b32_dpp v117, v68 row_ror:1 row_mask:0xf bank_mask:0xf
	v_mov_b32_dpp v103, v68 row_ror:2 row_mask:0xf bank_mask:0xf
	v_mov_b32_dpp v118, v69 row_ror:1 row_mask:0xf bank_mask:0xf
	v_mov_b32_dpp v102, v69 row_ror:2 row_mask:0xf bank_mask:0xf
	v_cmp_gt_u32_e64 s[42:43], 2, v108
	v_lshl_add_u64 v[10:11], s[96:97], 0, v[22:23]
	v_lshl_add_u64 v[12:13], s[62:63], 0, v[22:23]
	global_load_dwordx4 v[18:21], v[10:11], off
	global_load_dwordx4 v[14:17], v[12:13], off
	v_lshl_add_u64 v[10:11], s[64:65], 0, v[22:23]
	v_lshl_add_u64 v[22:23], s[66:67], 0, v[22:23]
	global_load_dwordx4 v[10:13], v[10:11], off
	s_nop 1
	global_load_dwordx4 v[22:25], v[22:23], off
	v_mov_b32_dpp v70, v42 row_ror:1 row_mask:0xf bank_mask:0xf
	v_mov_b32_dpp v76, v42 row_ror:2 row_mask:0xf bank_mask:0xf
	v_mov_b32_dpp v71, v43 row_ror:1 row_mask:0xf bank_mask:0xf
	v_mov_b32_dpp v77, v43 row_ror:2 row_mask:0xf bank_mask:0xf
	v_mov_b32_dpp v74, v72 row_ror:1 row_mask:0xf bank_mask:0xf
	v_mov_b32_dpp v78, v72 row_ror:2 row_mask:0xf bank_mask:0xf
	v_mov_b32_dpp v75, v73 row_ror:1 row_mask:0xf bank_mask:0xf
	v_mov_b32_dpp v79, v73 row_ror:2 row_mask:0xf bank_mask:0xf
	s_and_saveexec_b64 s[0:1], s[42:43]
	s_xor_b64 s[0:1], exec, s[0:1]
	s_or_saveexec_b64 s[0:1], s[0:1]
	v_mov_b64_e32 v[106:107], v[98:99]
	v_mov_b64_e32 v[104:105], v[96:97]
	s_xor_b64 exec, exec, s[0:1]
	s_cbranch_execz .Lcg_skip3
	s_waitcnt vmcnt(4)
	v_pk_fma_f32 v[46:47], v[28:29], v[90:91], v[40:41] op_sel:[0,1,0] op_sel_hi:[1,0,1]
	v_mov_b64_e32 v[106:107], v[94:95]
	v_pk_fma_f32 v[46:47], v[32:33], v[80:81], v[46:47]
	v_mov_b64_e32 v[104:105], v[92:93]
	v_pk_fma_f32 v[46:47], v[84:85], v[36:37], v[46:47]
	v_pk_fma_f32 v[84:85], v[26:27], v[86:87], v[38:39] op_sel:[0,1,0] op_sel_hi:[1,0,1]
	v_pk_fma_f32 v[84:85], v[30:31], v[66:67], v[84:85]
	v_pk_fma_f32 v[44:45], v[44:45], v[34:35], v[84:85]
	v_pk_mul_f32 v[86:87], v[46:47], s[98:99] op_sel_hi:[1,0]
	v_exp_f32_e32 v86, v86
	v_exp_f32_e32 v87, v87
	s_nop 0
	v_pk_add_f32 v[86:87], v[86:87], 1.0 op_sel_hi:[1,0]
	v_rcp_f32_e32 v86, v86
	v_rcp_f32_e32 v87, v87
	s_nop 0
	v_pk_mul_f32 v[46:47], v[46:47], v[86:87]
	s_waitcnt vmcnt(0)
	v_pk_fma_f32 v[86:87], v[18:19], v[76:77], v[22:23]
	v_add_u32_e32 v53, 0x80, v56
	v_pk_fma_f32 v[86:87], v[14:15], v[70:71], v[86:87]
	v_pk_mul_f32 v[84:85], v[44:45], s[98:99] op_sel_hi:[1,0]
	v_exp_f32_e32 v84, v84
	v_exp_f32_e32 v85, v85
	s_nop 0
	v_pk_add_f32 v[84:85], v[84:85], 1.0 op_sel_hi:[1,0]
	v_rcp_f32_e32 v84, v84
	v_rcp_f32_e32 v85, v85
	s_nop 0
	v_pk_mul_f32 v[44:45], v[44:45], v[84:85]
	v_pk_fma_f32 v[42:43], v[42:43], v[10:11], v[86:87]
	v_pk_fma_f32 v[84:85], v[20:21], v[78:79], v[24:25]
	v_pk_mul_f32 v[42:43], v[44:45], v[42:43]
	v_mov_b64_e32 v[44:45], s[36:37]
	v_pk_fma_f32 v[84:85], v[16:17], v[74:75], v[84:85]
	v_mad_i64_i32 v[44:45], s[4:5], v53, s46, v[44:45]
	v_pk_fma_f32 v[72:73], v[72:73], v[12:13], v[84:85]
	v_lshl_add_u64 v[44:45], v[58:59], 1, v[44:45]
	v_mov_b64_e32 v[90:91], v[98:99]
	v_mov_b64_e32 v[86:87], v[96:97]
	v_mov_b64_e32 v[94:95], v[102:103]
	v_mov_b64_e32 v[92:93], v[100:101]
	v_pk_mul_f32 v[46:47], v[46:47], v[72:73]
	v_cvt_pk_bf16_f32 v42, v42, v43
	s_nop 0
	v_cvt_pk_bf16_f32 v43, v46, v47
	global_store_dwordx2 v[44:45], v[42:43], off
.LBB0_135:
	s_or_b64 exec, exec, s[0:1]
	v_cmp_eq_u32_e64 s[42:43], 0, v108
	v_add_u32_e32 v96, 0x90, v56
	v_add_u32_e32 v97, 0xa0, v56
	v_add_u32_e32 v98, 0xb0, v56
	v_cndmask_b32_e64 v43, v118, v115, s[42:43]
	v_cndmask_b32_e64 v42, v117, v114, s[42:43]
	s_waitcnt vmcnt(4)
	v_pk_fma_f32 v[44:45], v[28:29], v[94:95], v[40:41] op_sel:[0,1,0] op_sel_hi:[1,0,1]
	v_cndmask_b32_e64 v47, v116, v113, s[42:43]
	v_cndmask_b32_e64 v46, v57, v112, s[42:43]
	v_pk_fma_f32 v[56:57], v[26:27], v[92:93], v[38:39] op_sel:[0,1,0] op_sel_hi:[1,0,1]
	v_pk_fma_f32 v[42:43], v[32:33], v[42:43], v[44:45]
	v_pk_fma_f32 v[46:47], v[30:31], v[46:47], v[56:57]
	v_pk_fma_f32 v[42:43], v[68:69], v[36:37], v[42:43]
	v_pk_fma_f32 v[46:47], v[64:65], v[34:35], v[46:47]
	v_cndmask_b32_e64 v65, v115, v111, s[42:43]
	v_cndmask_b32_e64 v64, v114, v110, s[42:43]
	v_pk_fma_f32 v[68:69], v[28:29], v[106:107], v[40:41] op_sel:[0,1,0] op_sel_hi:[1,0,1]
	v_cndmask_b32_e64 v81, v111, v81, s[42:43]
	v_cndmask_b32_e64 v80, v110, v80, s[42:43]
	v_pk_fma_f32 v[28:29], v[28:29], v[90:91], v[40:41] op_sel:[0,1,0] op_sel_hi:[1,0,1]
	v_pk_fma_f32 v[64:65], v[32:33], v[64:65], v[68:69]
	v_pk_fma_f32 v[28:29], v[32:33], v[80:81], v[28:29]
	v_pk_fma_f32 v[64:65], v[88:89], v[36:37], v[64:65]
	v_pk_fma_f32 v[84:85], v[26:27], v[104:105], v[38:39] op_sel:[0,1,0] op_sel_hi:[1,0,1]
	v_pk_fma_f32 v[28:29], v[60:61], v[36:37], v[28:29]
	v_cndmask_b32_e64 v37, v109, v67, s[42:43]
	v_cndmask_b32_e64 v36, v0, v66, s[42:43]
	v_pk_fma_f32 v[26:27], v[26:27], v[86:87], v[38:39] op_sel:[0,1,0] op_sel_hi:[1,0,1]
	v_cndmask_b32_e64 v72, v112, v0, s[42:43]
	v_pk_fma_f32 v[26:27], v[30:31], v[36:37], v[26:27]
	v_pk_fma_f32 v[26:27], v[54:55], v[34:35], v[26:27]
	v_cndmask_b32_e64 v73, v113, v109, s[42:43]
	v_pk_fma_f32 v[72:73], v[30:31], v[72:73], v[84:85]
	v_pk_fma_f32 v[72:73], v[82:83], v[34:35], v[72:73]
	v_mov_b32_e32 v34, v62
	v_mov_b32_e32 v35, v62
	v_mov_b32_e32 v53, v52
	v_mov_b32_e32 v63, v62
	v_pk_mul_f32 v[4:5], v[4:5], v[34:35]
	v_mov_b32_e32 v34, v52
	v_mov_b32_e32 v35, v52
	v_pk_mul_f32 v[2:3], v[2:3], v[62:63]
	v_pk_mul_f32 v[8:9], v[8:9], v[34:35]
	v_pk_mul_f32 v[6:7], v[6:7], v[52:53]
	s_nop 1
	v_mov_b32_dpp v52, v6 row_ror:2 row_mask:0xf bank_mask:0xf
	v_mov_b32_dpp v54, v7 row_ror:2 row_mask:0xf bank_mask:0xf
	v_mov_b32_dpp v60, v8 row_ror:2 row_mask:0xf bank_mask:0xf
	v_mov_b32_dpp v62, v9 row_ror:2 row_mask:0xf bank_mask:0xf
	v_mov_b32_dpp v0, v6 row_ror:1 row_mask:0xf bank_mask:0xf
	v_mov_b32_dpp v53, v7 row_ror:1 row_mask:0xf bank_mask:0xf
	v_mov_b32_dpp v55, v8 row_ror:1 row_mask:0xf bank_mask:0xf
	v_mov_b32_dpp v61, v9 row_ror:1 row_mask:0xf bank_mask:0xf
	v_cndmask_b32_e32 v34, v76, v52, vcc
	v_cndmask_b32_e32 v35, v77, v54, vcc
	v_cndmask_b32_e32 v36, v78, v60, vcc
	v_cndmask_b32_e32 v37, v79, v62, vcc
	v_cndmask_b32_e64 v38, v0, v70, s[42:43]
	v_cndmask_b32_e64 v39, v53, v71, s[42:43]
	v_cndmask_b32_e64 v40, v55, v74, s[42:43]
	v_cndmask_b32_e64 v41, v61, v75, s[42:43]
	v_pk_mul_f32 v[30:31], v[26:27], s[98:99] op_sel_hi:[1,0]
	v_pk_mul_f32 v[32:33], v[28:29], s[98:99] op_sel_hi:[1,0]
	v_exp_f32_e32 v30, v30
	v_exp_f32_e32 v31, v31
	v_exp_f32_e32 v32, v32
	v_exp_f32_e32 v33, v33
	v_pk_add_f32 v[30:31], v[30:31], 1.0 op_sel_hi:[1,0]
	v_pk_add_f32 v[32:33], v[32:33], 1.0 op_sel_hi:[1,0]
	v_rcp_f32_e32 v30, v30
	v_rcp_f32_e32 v31, v31
	v_rcp_f32_e32 v32, v32
	v_rcp_f32_e32 v33, v33
	v_pk_mul_f32 v[26:27], v[26:27], v[30:31]
	v_pk_mul_f32 v[28:29], v[28:29], v[32:33]
	s_waitcnt vmcnt(1)
	v_pk_fma_f32 v[30:31], v[20:21], v[36:37], v[24:25]
	v_pk_fma_f32 v[32:33], v[18:19], v[34:35], v[22:23]
	v_pk_fma_f32 v[30:31], v[16:17], v[40:41], v[30:31]
	v_pk_fma_f32 v[32:33], v[14:15], v[38:39], v[32:33]
	v_pk_fma_f32 v[8:9], v[8:9], v[12:13], v[30:31]
	v_pk_fma_f32 v[6:7], v[6:7], v[10:11], v[32:33]
	v_pk_mul_f32 v[8:9], v[28:29], v[8:9]
	v_pk_mul_f32 v[6:7], v[26:27], v[6:7]
	v_cvt_pk_bf16_f32 v6, v6, v7
	v_cvt_pk_bf16_f32 v7, v8, v9
	v_mov_b64_e32 v[8:9], s[36:37]
	v_mad_i64_i32 v[26:27], s[0:1], v96, s46, v[8:9]
	v_lshlrev_b64 v[28:29], 1, v[58:59]
	s_nop 1
	v_lshl_add_u64 v[26:27], v[26:27], 0, v[28:29]
	v_mov_b32_dpp v39, v2 row_ror:2 row_mask:0xf bank_mask:0xf
	v_mov_b32_dpp v41, v3 row_ror:2 row_mask:0xf bank_mask:0xf
	v_mov_b32_dpp v59, v4 row_ror:2 row_mask:0xf bank_mask:0xf
	v_mov_b32_dpp v66, v5 row_ror:2 row_mask:0xf bank_mask:0xf
	global_store_dwordx2 v[26:27], v[6:7], off
	v_mov_b32_dpp v38, v2 row_ror:1 row_mask:0xf bank_mask:0xf
	v_mov_b32_dpp v40, v3 row_ror:1 row_mask:0xf bank_mask:0xf
	v_mov_b32_dpp v58, v4 row_ror:1 row_mask:0xf bank_mask:0xf
	v_mov_b32_dpp v63, v5 row_ror:1 row_mask:0xf bank_mask:0xf
	v_cndmask_b32_e32 v6, v52, v39, vcc
	v_cndmask_b32_e32 v7, v54, v41, vcc
	v_cndmask_b32_e32 v26, v60, v59, vcc
	v_cndmask_b32_e32 v27, v62, v66, vcc
	v_cndmask_b32_e64 v30, v38, v0, s[42:43]
	v_cndmask_b32_e64 v31, v40, v53, s[42:43]
	v_cndmask_b32_e64 v32, v58, v55, s[42:43]
	v_cndmask_b32_e64 v33, v63, v61, s[42:43]
	v_pk_fma_f32 v[26:27], v[20:21], v[26:27], v[24:25]
	v_pk_fma_f32 v[6:7], v[18:19], v[6:7], v[22:23]
	v_pk_fma_f32 v[26:27], v[16:17], v[32:33], v[26:27]
	v_pk_fma_f32 v[6:7], v[14:15], v[30:31], v[6:7]
	v_pk_mul_f32 v[82:83], v[72:73], s[98:99] op_sel_hi:[1,0]
	v_pk_mul_f32 v[68:69], v[64:65], s[98:99] op_sel_hi:[1,0]
	v_exp_f32_e32 v82, v82
	v_exp_f32_e32 v83, v83
	v_exp_f32_e32 v68, v68
	v_exp_f32_e32 v69, v69
	v_pk_add_f32 v[82:83], v[82:83], 1.0 op_sel_hi:[1,0]
	v_pk_add_f32 v[68:69], v[68:69], 1.0 op_sel_hi:[1,0]
	v_rcp_f32_e32 v82, v82
	v_rcp_f32_e32 v83, v83
	v_rcp_f32_e32 v68, v68
	v_rcp_f32_e32 v69, v69
	v_pk_mul_f32 v[34:35], v[72:73], v[82:83]
	v_pk_mul_f32 v[36:37], v[64:65], v[68:69]
	v_pk_fma_f32 v[4:5], v[4:5], v[12:13], v[26:27]
	v_pk_fma_f32 v[2:3], v[2:3], v[10:11], v[6:7]
	v_pk_mul_f32 v[4:5], v[36:37], v[4:5]
	v_pk_mul_f32 v[2:3], v[34:35], v[2:3]
	v_cvt_pk_bf16_f32 v2, v2, v3
	v_cvt_pk_bf16_f32 v3, v4, v5
	v_mad_i64_i32 v[4:5], s[0:1], v97, s46, v[8:9]
	v_lshl_add_u64 v[4:5], v[4:5], 0, v[28:29]
	global_store_dwordx2 v[4:5], v[2:3], off
	s_nop 1
	v_mov_b32_dpp v2, v50 row_ror:2 row_mask:0xf bank_mask:0xf
	v_mov_b32_dpp v3, v51 row_ror:2 row_mask:0xf bank_mask:0xf
	v_mov_b32_dpp v4, v48 row_ror:2 row_mask:0xf bank_mask:0xf
	v_mov_b32_dpp v5, v49 row_ror:2 row_mask:0xf bank_mask:0xf
	v_mov_b32_dpp v0, v50 row_ror:1 row_mask:0xf bank_mask:0xf
	v_mov_b32_dpp v7, v51 row_ror:1 row_mask:0xf bank_mask:0xf
	v_mov_b32_dpp v26, v48 row_ror:1 row_mask:0xf bank_mask:0xf
	v_mov_b32_dpp v27, v49 row_ror:1 row_mask:0xf bank_mask:0xf
	v_cndmask_b32_e32 v2, v39, v2, vcc
	v_cndmask_b32_e32 v3, v41, v3, vcc
	v_cndmask_b32_e32 v4, v59, v4, vcc
	v_cndmask_b32_e32 v5, v66, v5, vcc
	v_cndmask_b32_e64 v6, v0, v38, s[42:43]
	v_cndmask_b32_e64 v7, v7, v40, s[42:43]
	v_cndmask_b32_e64 v26, v26, v58, s[42:43]
	v_cndmask_b32_e64 v27, v27, v63, s[42:43]
	v_pk_fma_f32 v[2:3], v[18:19], v[2:3], v[22:23]
	v_pk_fma_f32 v[4:5], v[20:21], v[4:5], v[24:25]
	v_pk_fma_f32 v[2:3], v[14:15], v[6:7], v[2:3]
	v_pk_fma_f32 v[4:5], v[16:17], v[26:27], v[4:5]
	v_pk_mul_f32 v[56:57], v[46:47], s[98:99] op_sel_hi:[1,0]
	v_pk_mul_f32 v[44:45], v[42:43], s[98:99] op_sel_hi:[1,0]
	v_exp_f32_e32 v56, v56
	v_exp_f32_e32 v57, v57
	v_exp_f32_e32 v44, v44
	v_exp_f32_e32 v45, v45
	v_pk_add_f32 v[56:57], v[56:57], 1.0 op_sel_hi:[1,0]
	v_pk_add_f32 v[44:45], v[44:45], 1.0 op_sel_hi:[1,0]
	v_rcp_f32_e32 v56, v56
	v_rcp_f32_e32 v57, v57
	v_rcp_f32_e32 v44, v44
	v_rcp_f32_e32 v45, v45
	v_pk_mul_f32 v[30:31], v[46:47], v[56:57]
	v_pk_mul_f32 v[32:33], v[42:43], v[44:45]
	v_pk_fma_f32 v[2:3], v[50:51], v[10:11], v[2:3]
	v_pk_fma_f32 v[4:5], v[48:49], v[12:13], v[4:5]
	v_pk_mul_f32 v[2:3], v[30:31], v[2:3]
	v_pk_mul_f32 v[4:5], v[32:33], v[4:5]
	v_cvt_pk_bf16_f32 v2, v2, v3
	s_nop 0
	v_cvt_pk_bf16_f32 v3, v4, v5
	v_mad_i64_i32 v[4:5], s[0:1], v98, s46, v[8:9]
	v_lshl_add_u64 v[4:5], v[4:5], 0, v[28:29]
	global_store_dwordx2 v[4:5], v[2:3], off
	s_andn2_b64 vcc, exec, s[40:41]
	s_mov_b64 s[0:1], -1
	s_cbranch_vccnz .LBB0_102
	s_andn2_b64 vcc, exec, s[30:31]
	s_cbranch_vccnz .LBB0_101
	s_barrier
	s_branch .LBB0_101
